# default cache policy (no nt) on the 16-byte f32 row stores too, on top of v25
# baseline (speedup 1.0000x reference)
; #define GAS __attribute__((address_space(1)))
; DI unsigned pk2(float lo, float hi) { f32x2_t v = {lo, hi}; bf16x2_t b = __builtin_convertvector(v, bf16x2_t); return __builtin_bit_cast(unsigned, b); }
; DI float bflo(unsigned w) { return __uint_as_float(w << 16); }
; DI float bfhi(unsigned w) { return __uint_as_float(w & 0xffff0000u); }
; DI void phase_e(const Ctx& C, int nslab, int has_post, int pl, int ps, float pw, int has_pre, int ql, int qs, int nrows,
;                 const GAS float* xsrc, const GAS float* csrc, GAS float* xdst, GAS float* cdst, bool xs16, bool xd16) {
;     ...
;             f32x4 y[4]; float ss = 0.f;
; #pragma unroll
;             for (int j = 0; j < 4; ++j) {
;                 if (isx || nslab == 0) { y[j] = (f32x4){bflo(yw[j].x), bfhi(yw[j].x), bflo(yw[j].y), bfhi(yw[j].y)}; }
;                 else { y[j] = (f32x4){0.f, 0.f, 0.f, 0.f};
;                     for (int s = 0; s < nslab; ++s) { const u32x2 w = *(const GAS u32x2*)(YS + ((size_t)s * MC + (row - MX)) * 1024 + 256 * j + 4 * lane); y[j] += (f32x4){bflo(w.x), bfhi(w.x), bflo(w.y), bfhi(w.y)}; } }
;                 ss += (y[j][0] * y[j][0] + y[j][1] * y[j][1]) + (y[j][2] * y[j][2] + y[j][3] * y[j][3]); }
;             const float r = rsqrtf(wave_sum(ss) * (1.0f / 1024.0f) + EPS);
;             if (isx && xd16) { GAS bf16* d16 = (GAS bf16*)xdst + (size_t)row * 1024;
; #pragma unroll
;                 for (int j = 0; j < 4; ++j) { v[j] += pw * gt[j] * ((y[j] * r) * gpo[j]); u32x2 w; w.x = pk2(v[j][0], v[j][1]); w.y = pk2(v[j][2], v[j][3]); __builtin_nontemporal_store(w, (GAS u32x2*)(d16 + 256 * j + 4 * lane));
;                     v[j] = (f32x4){bflo(w.x), bfhi(w.x), bflo(w.y), bfhi(w.y)}; }
;             } else { GAS float* dst = isx ? xdst + (size_t)row * 1024 : cdst + (size_t)(row - MX) * 1024;
; #pragma unroll
;                 for (int j = 0; j < 4; ++j) { v[j] += pw * gt[j] * ((y[j] * r) * gpo[j]); __builtin_nontemporal_store(v[j], (GAS f32x4*)(dst + 256 * j + 4 * lane)); } }
.LBB0_446:
	v_mul_f32_e32 v130, v141, v141
	v_mul_f32_e32 v131, v139, v139
	v_fmac_f32_e32 v130, v140, v140
	v_fmac_f32_e32 v131, v138, v138
	v_add_f32_e32 v130, v130, v131
	v_mul_f32_e32 v131, v171, v171
	v_mul_f32_e32 v132, v173, v173
	v_fmac_f32_e32 v131, v170, v170
	v_fmac_f32_e32 v132, v172, v172
	v_add_f32_e32 v131, v131, v132
	v_add_f32_e32 v130, v130, v131
	v_mul_f32_e32 v131, v175, v175
	v_mul_f32_e32 v132, v177, v177
	v_fmac_f32_e32 v131, v174, v174
	v_fmac_f32_e32 v132, v176, v176
	v_add_f32_e32 v131, v131, v132
	v_add_f32_e32 v136, v130, v131
	v_pk_mul_f32 v[130:131], v[180:181], v[180:181]
	v_pk_mul_f32 v[132:133], v[178:179], v[178:179]
	s_and_b64 s[0:1], exec, s[0:1]
	v_pk_mov_b32 v[134:135], v[132:133], v[130:131] op_sel:[1,0]
	v_mov_b32_e32 v133, v131
	v_pk_add_f32 v[130:131], v[134:135], v[132:133]
	s_ashr_i32 s13, s12, 31
	v_add_f32_e32 v130, v130, v131
	v_add_f32_e32 v130, v136, v130
	s_nop 1
	v_add_f32_dpp v130, v130, v130 quad_perm:[1,0,3,2] row_mask:0xf bank_mask:0xf
	s_nop 1
	v_add_f32_dpp v130, v130, v130 quad_perm:[2,3,0,1] row_mask:0xf bank_mask:0xf
	s_nop 1
	v_add_f32_dpp v130, v130, v130 row_half_mirror row_mask:0xf bank_mask:0xf
	s_nop 1
	v_add_f32_dpp v130, v130, v130 row_mirror row_mask:0xf bank_mask:0xf
	s_nop 1
	v_add_f32_dpp v130, v130, v130 row_bcast:15 row_mask:0xa bank_mask:0xf
	s_nop 1
	v_add_f32_dpp v130, v130, v130 row_bcast:31 row_mask:0xc bank_mask:0xf
	s_nop 0
	v_readlane_b32 s64, v130, 63
	s_nop 1
	v_mov_b32_e32 v132, s64
	s_waitcnt lgkmcnt(0)
	s_mov_b64 s[22:23], -1
	s_waitcnt vmcnt(7)
	v_pk_mul_f32 v[188:189], v[98:99], 0.5 op_sel_hi:[1,0]
	s_waitcnt vmcnt(6)
	v_pk_mul_f32 v[186:187], v[102:103], 0.5 op_sel_hi:[1,0]
	s_waitcnt vmcnt(4)
	v_pk_mul_f32 v[184:185], v[106:107], 0.5 op_sel_hi:[1,0]
	v_pk_mul_f32 v[130:131], v[96:97], 0.5 op_sel_hi:[1,0]
	v_fmamk_f32 v132, v132, 0x3a800000, v197
	v_mul_f32_e32 v133, 0x4b800000, v132
	v_cmp_gt_f32_e32 vcc, s47, v132
	s_nop 1
	v_cndmask_b32_e32 v132, v132, v133, vcc
	v_rsq_f32_e32 v134, v132
	v_pk_mul_f32 v[132:133], v[94:95], 0.5 op_sel_hi:[1,0]
	v_mul_f32_e32 v135, 0x45800000, v134
	v_cndmask_b32_e32 v182, v134, v135, vcc
	v_mov_b32_e32 v183, v182
	v_pk_mul_f32 v[134:135], v[138:139], v[182:183] op_sel_hi:[1,0]
	v_pk_mul_f32 v[136:137], v[140:141], v[182:183] op_sel_hi:[1,0]
	v_pk_mul_f32 v[134:135], v[4:5], v[134:135]
	v_pk_mul_f32 v[136:137], v[2:3], v[136:137]
	v_pk_fma_f32 v[128:129], v[130:131], v[134:135], v[128:129]
	v_pk_fma_f32 v[126:127], v[132:133], v[136:137], v[126:127]
	s_mov_b64 vcc, s[0:1]
	s_cbranch_vccz .LBB0_448
	v_mov_b32_e32 v138, v182
	v_mov_b32_e32 v139, v182
	v_pk_mul_f32 v[132:133], v[172:173], v[138:139]
	v_pk_mul_f32 v[134:135], v[170:171], v[182:183]
	v_pk_mul_f32 v[130:131], v[100:101], 0.5 op_sel_hi:[1,0]
	v_pk_mul_f32 v[132:133], v[8:9], v[132:133]
	v_pk_mul_f32 v[134:135], v[6:7], v[134:135]
	v_pk_mul_f32 v[136:137], v[176:177], v[138:139]
	v_pk_mul_f32 v[140:141], v[174:175], v[182:183]
	v_pk_fma_f32 v[132:133], v[130:131], v[132:133], v[60:61]
	v_pk_fma_f32 v[130:131], v[188:189], v[134:135], v[58:59]
	v_pk_mul_f32 v[134:135], v[104:105], 0.5 op_sel_hi:[1,0]
	v_pk_mul_f32 v[136:137], v[20:21], v[136:137]
	v_pk_mul_f32 v[140:141], v[18:19], v[140:141]
	v_pk_mul_f32 v[138:139], v[180:181], v[138:139]
	v_pk_mul_f32 v[200:201], v[178:179], v[182:183]
	s_lshl_b64 s[0:1], s[6:7], 12
	v_pk_fma_f32 v[136:137], v[134:135], v[136:137], v[56:57]
	v_pk_fma_f32 v[134:135], v[186:187], v[140:141], v[54:55]
	v_pk_mul_f32 v[140:141], v[108:109], 0.5 op_sel_hi:[1,0]
	v_pk_mul_f32 v[138:139], v[24:25], v[138:139]
	v_pk_mul_f32 v[200:201], v[22:23], v[200:201]
	v_lshl_add_u64 v[198:199], v[160:161], 0, s[0:1]
	v_pk_fma_f32 v[140:141], v[140:141], v[138:139], v[52:53]
	v_pk_fma_f32 v[138:139], v[184:185], v[200:201], v[50:51]
	global_store_dwordx4 v[198:199], v[126:129], off
	global_store_dwordx4 v[198:199], v[130:133], off offset:1024
	global_store_dwordx4 v[198:199], v[134:137], off offset:2048
	global_store_dwordx4 v[198:199], v[138:141], off offset:3072
	s_lshl_b64 s[2:3], s[12:13], 11
	s_mov_b64 s[22:23], 0

; #define GAS __attribute__((address_space(1)))
; DI unsigned pk2(float lo, float hi) { f32x2_t v = {lo, hi}; bf16x2_t b = __builtin_convertvector(v, bf16x2_t); return __builtin_bit_cast(unsigned, b); }
; DI float bflo(unsigned w) { return __uint_as_float(w << 16); }
; DI float bfhi(unsigned w) { return __uint_as_float(w & 0xffff0000u); }
; DI void phase_e(const Ctx& C, int nslab, int has_post, int pl, int ps, float pw, int has_pre, int ql, int qs, int nrows,
;                 const GAS float* xsrc, const GAS float* csrc, GAS float* xdst, GAS float* cdst, bool xs16, bool xd16) {
;     ...
;             f32x4 y[4]; float ss = 0.f;
; #pragma unroll
;             for (int j = 0; j < 4; ++j) {
;                 if (isx || nslab == 0) { y[j] = (f32x4){bflo(yw[j].x), bfhi(yw[j].x), bflo(yw[j].y), bfhi(yw[j].y)}; }
;                 else { y[j] = (f32x4){0.f, 0.f, 0.f, 0.f};
;                     for (int s = 0; s < nslab; ++s) { const u32x2 w = *(const GAS u32x2*)(YS + ((size_t)s * MC + (row - MX)) * 1024 + 256 * j + 4 * lane); y[j] += (f32x4){bflo(w.x), bfhi(w.x), bflo(w.y), bfhi(w.y)}; } }
;                 ss += (y[j][0] * y[j][0] + y[j][1] * y[j][1]) + (y[j][2] * y[j][2] + y[j][3] * y[j][3]); }
;             const float r = rsqrtf(wave_sum(ss) * (1.0f / 1024.0f) + EPS);
;             if (isx && xd16) { GAS bf16* d16 = (GAS bf16*)xdst + (size_t)row * 1024;
; #pragma unroll
;                 for (int j = 0; j < 4; ++j) { v[j] += pw * gt[j] * ((y[j] * r) * gpo[j]); u32x2 w; w.x = pk2(v[j][0], v[j][1]); w.y = pk2(v[j][2], v[j][3]); __builtin_nontemporal_store(w, (GAS u32x2*)(d16 + 256 * j + 4 * lane));
;                     v[j] = (f32x4){bflo(w.x), bfhi(w.x), bflo(w.y), bfhi(w.y)}; }
;             } else { GAS float* dst = isx ? xdst + (size_t)row * 1024 : cdst + (size_t)(row - MX) * 1024;
; #pragma unroll
;                 for (int j = 0; j < 4; ++j) { v[j] += pw * gt[j] * ((y[j] * r) * gpo[j]); __builtin_nontemporal_store(v[j], (GAS f32x4*)(dst + 256 * j + 4 * lane)); } }
.Lrow1_446:
	v_mul_f32_e32 v130, v141, v141
	v_mul_f32_e32 v131, v139, v139
	v_fmac_f32_e32 v130, v140, v140
	v_fmac_f32_e32 v131, v138, v138
	v_add_f32_e32 v130, v130, v131
	v_mul_f32_e32 v131, v171, v171
	v_mul_f32_e32 v132, v173, v173
	v_fmac_f32_e32 v131, v170, v170
	v_fmac_f32_e32 v132, v172, v172
	v_add_f32_e32 v131, v131, v132
	v_add_f32_e32 v130, v130, v131
	v_mul_f32_e32 v131, v175, v175
	v_mul_f32_e32 v132, v177, v177
	v_fmac_f32_e32 v131, v174, v174
	v_fmac_f32_e32 v132, v176, v176
	v_add_f32_e32 v131, v131, v132
	v_add_f32_e32 v136, v130, v131
	v_pk_mul_f32 v[130:131], v[180:181], v[180:181]
	v_pk_mul_f32 v[132:133], v[178:179], v[178:179]
	s_and_b64 s[0:1], exec, s[0:1]
	v_pk_mov_b32 v[134:135], v[132:133], v[130:131] op_sel:[1,0]
	v_mov_b32_e32 v133, v131
	v_pk_add_f32 v[130:131], v[134:135], v[132:133]
	s_ashr_i32 s13, s12, 31
	v_add_f32_e32 v130, v130, v131
	v_add_f32_e32 v130, v136, v130
	s_nop 1
	v_add_f32_dpp v130, v130, v130 quad_perm:[1,0,3,2] row_mask:0xf bank_mask:0xf
	s_nop 1
	v_add_f32_dpp v130, v130, v130 quad_perm:[2,3,0,1] row_mask:0xf bank_mask:0xf
	s_nop 1
	v_add_f32_dpp v130, v130, v130 row_half_mirror row_mask:0xf bank_mask:0xf
	s_nop 1
	v_add_f32_dpp v130, v130, v130 row_mirror row_mask:0xf bank_mask:0xf
	s_nop 1
	v_add_f32_dpp v130, v130, v130 row_bcast:15 row_mask:0xa bank_mask:0xf
	s_nop 1
	v_add_f32_dpp v130, v130, v130 row_bcast:31 row_mask:0xc bank_mask:0xf
	s_nop 0
	v_readlane_b32 s64, v130, 63
	s_nop 1
	v_mov_b32_e32 v132, s64
	s_waitcnt lgkmcnt(0)
	s_mov_b64 s[22:23], -1
	s_waitcnt vmcnt(7)
	v_pk_mul_f32 v[188:189], v[98:99], 0.5 op_sel_hi:[1,0]
	s_waitcnt vmcnt(6)
	v_pk_mul_f32 v[186:187], v[102:103], 0.5 op_sel_hi:[1,0]
	s_waitcnt vmcnt(4)
	v_pk_mul_f32 v[184:185], v[106:107], 0.5 op_sel_hi:[1,0]
	v_pk_mul_f32 v[130:131], v[96:97], 0.5 op_sel_hi:[1,0]
	v_fmamk_f32 v132, v132, 0x3a800000, v197
	v_mul_f32_e32 v133, 0x4b800000, v132
	v_cmp_gt_f32_e32 vcc, s47, v132
	s_nop 1
	v_cndmask_b32_e32 v132, v132, v133, vcc
	v_rsq_f32_e32 v134, v132
	v_pk_mul_f32 v[132:133], v[94:95], 0.5 op_sel_hi:[1,0]
	v_mul_f32_e32 v135, 0x45800000, v134
	v_cndmask_b32_e32 v182, v134, v135, vcc
	v_mov_b32_e32 v183, v182
	v_pk_mul_f32 v[134:135], v[138:139], v[182:183] op_sel_hi:[1,0]
	v_pk_mul_f32 v[136:137], v[140:141], v[182:183] op_sel_hi:[1,0]
	v_pk_mul_f32 v[134:135], v[4:5], v[134:135]
	v_pk_mul_f32 v[136:137], v[2:3], v[136:137]
	v_pk_fma_f32 v[36:37], v[130:131], v[134:135], v[36:37]
	v_pk_fma_f32 v[34:35], v[132:133], v[136:137], v[34:35]
	s_mov_b64 vcc, s[0:1]
	s_cbranch_vccz .Lrow1_448
	v_mov_b32_e32 v138, v182
	v_mov_b32_e32 v139, v182
	v_pk_mul_f32 v[132:133], v[172:173], v[138:139]
	v_pk_mul_f32 v[134:135], v[170:171], v[182:183]
	v_pk_mul_f32 v[130:131], v[100:101], 0.5 op_sel_hi:[1,0]
	v_pk_mul_f32 v[132:133], v[8:9], v[132:133]
	v_pk_mul_f32 v[134:135], v[6:7], v[134:135]
	v_pk_mul_f32 v[136:137], v[176:177], v[138:139]
	v_pk_mul_f32 v[140:141], v[174:175], v[182:183]
	v_pk_fma_f32 v[132:133], v[130:131], v[132:133], v[40:41]
	v_pk_fma_f32 v[130:131], v[188:189], v[134:135], v[38:39]
	v_pk_mul_f32 v[134:135], v[104:105], 0.5 op_sel_hi:[1,0]
	v_pk_mul_f32 v[136:137], v[20:21], v[136:137]
	v_pk_mul_f32 v[140:141], v[18:19], v[140:141]
	v_pk_mul_f32 v[138:139], v[180:181], v[138:139]
	v_pk_mul_f32 v[200:201], v[178:179], v[182:183]
	s_lshl_b64 s[0:1], s[6:7], 12
	v_pk_fma_f32 v[136:137], v[134:135], v[136:137], v[44:45]
	v_pk_fma_f32 v[134:135], v[186:187], v[140:141], v[42:43]
	v_pk_mul_f32 v[140:141], v[108:109], 0.5 op_sel_hi:[1,0]
	v_pk_mul_f32 v[138:139], v[24:25], v[138:139]
	v_pk_mul_f32 v[200:201], v[22:23], v[200:201]
	v_lshl_add_u64 v[198:199], v[160:161], 0, s[0:1]
	v_pk_fma_f32 v[140:141], v[140:141], v[138:139], v[48:49]
	v_pk_fma_f32 v[138:139], v[184:185], v[200:201], v[46:47]
	global_store_dwordx4 v[198:199], v[34:37], off
	global_store_dwordx4 v[198:199], v[130:133], off offset:1024
	global_store_dwordx4 v[198:199], v[134:137], off offset:2048
	global_store_dwordx4 v[198:199], v[138:141], off offset:3072
	s_lshl_b64 s[2:3], s[12:13], 11
	s_mov_b64 s[22:23], 0

; #define GAS __attribute__((address_space(1)))
; DI unsigned pk2(float lo, float hi) { f32x2_t v = {lo, hi}; bf16x2_t b = __builtin_convertvector(v, bf16x2_t); return __builtin_bit_cast(unsigned, b); }
; DI float bflo(unsigned w) { return __uint_as_float(w << 16); }
; DI float bfhi(unsigned w) { return __uint_as_float(w & 0xffff0000u); }
; DI void phase_e(const Ctx& C, int nslab, int has_post, int pl, int ps, float pw, int has_pre, int ql, int qs, int nrows,
;                 const GAS float* xsrc, const GAS float* csrc, GAS float* xdst, GAS float* cdst, bool xs16, bool xd16) {
;     ...
;             f32x4 y[4]; float ss = 0.f;
; #pragma unroll
;             for (int j = 0; j < 4; ++j) {
;                 if (isx || nslab == 0) { y[j] = (f32x4){bflo(yw[j].x), bfhi(yw[j].x), bflo(yw[j].y), bfhi(yw[j].y)}; }
;                 else { y[j] = (f32x4){0.f, 0.f, 0.f, 0.f};
;                     for (int s = 0; s < nslab; ++s) { const u32x2 w = *(const GAS u32x2*)(YS + ((size_t)s * MC + (row - MX)) * 1024 + 256 * j + 4 * lane); y[j] += (f32x4){bflo(w.x), bfhi(w.x), bflo(w.y), bfhi(w.y)}; } }
;                 ss += (y[j][0] * y[j][0] + y[j][1] * y[j][1]) + (y[j][2] * y[j][2] + y[j][3] * y[j][3]); }
;             const float r = rsqrtf(wave_sum(ss) * (1.0f / 1024.0f) + EPS);
;             if (isx && xd16) { GAS bf16* d16 = (GAS bf16*)xdst + (size_t)row * 1024;
; #pragma unroll
;                 for (int j = 0; j < 4; ++j) { v[j] += pw * gt[j] * ((y[j] * r) * gpo[j]); u32x2 w; w.x = pk2(v[j][0], v[j][1]); w.y = pk2(v[j][2], v[j][3]); __builtin_nontemporal_store(w, (GAS u32x2*)(d16 + 256 * j + 4 * lane));
;                     v[j] = (f32x4){bflo(w.x), bfhi(w.x), bflo(w.y), bfhi(w.y)}; }
;             } else { GAS float* dst = isx ? xdst + (size_t)row * 1024 : cdst + (size_t)(row - MX) * 1024;
; #pragma unroll
;                 for (int j = 0; j < 4; ++j) { v[j] += pw * gt[j] * ((y[j] * r) * gpo[j]); __builtin_nontemporal_store(v[j], (GAS f32x4*)(dst + 256 * j + 4 * lane)); } }
.Lrow2_446:
	v_mul_f32_e32 v130, v141, v141
	v_mul_f32_e32 v131, v139, v139
	v_fmac_f32_e32 v130, v140, v140
	v_fmac_f32_e32 v131, v138, v138
	v_add_f32_e32 v130, v130, v131
	v_mul_f32_e32 v131, v171, v171
	v_mul_f32_e32 v132, v173, v173
	v_fmac_f32_e32 v131, v170, v170
	v_fmac_f32_e32 v132, v172, v172
	v_add_f32_e32 v131, v131, v132
	v_add_f32_e32 v130, v130, v131
	v_mul_f32_e32 v131, v175, v175
	v_mul_f32_e32 v132, v177, v177
	v_fmac_f32_e32 v131, v174, v174
	v_fmac_f32_e32 v132, v176, v176
	v_add_f32_e32 v131, v131, v132
	v_add_f32_e32 v136, v130, v131
	v_pk_mul_f32 v[130:131], v[180:181], v[180:181]
	v_pk_mul_f32 v[132:133], v[178:179], v[178:179]
	s_and_b64 s[0:1], exec, s[0:1]
	v_pk_mov_b32 v[134:135], v[132:133], v[130:131] op_sel:[1,0]
	v_mov_b32_e32 v133, v131
	v_pk_add_f32 v[130:131], v[134:135], v[132:133]
	s_ashr_i32 s13, s12, 31
	v_add_f32_e32 v130, v130, v131
	v_add_f32_e32 v130, v136, v130
	s_nop 1
	v_add_f32_dpp v130, v130, v130 quad_perm:[1,0,3,2] row_mask:0xf bank_mask:0xf
	s_nop 1
	v_add_f32_dpp v130, v130, v130 quad_perm:[2,3,0,1] row_mask:0xf bank_mask:0xf
	s_nop 1
	v_add_f32_dpp v130, v130, v130 row_half_mirror row_mask:0xf bank_mask:0xf
	s_nop 1
	v_add_f32_dpp v130, v130, v130 row_mirror row_mask:0xf bank_mask:0xf
	s_nop 1
	v_add_f32_dpp v130, v130, v130 row_bcast:15 row_mask:0xa bank_mask:0xf
	s_nop 1
	v_add_f32_dpp v130, v130, v130 row_bcast:31 row_mask:0xc bank_mask:0xf
	s_nop 0
	v_readlane_b32 s64, v130, 63
	s_nop 1
	v_mov_b32_e32 v132, s64
	s_waitcnt lgkmcnt(0)
	s_mov_b64 s[22:23], -1
	s_waitcnt vmcnt(7)
	v_pk_mul_f32 v[188:189], v[98:99], 0.5 op_sel_hi:[1,0]
	s_waitcnt vmcnt(6)
	v_pk_mul_f32 v[186:187], v[102:103], 0.5 op_sel_hi:[1,0]
	s_waitcnt vmcnt(4)
	v_pk_mul_f32 v[184:185], v[106:107], 0.5 op_sel_hi:[1,0]
	v_pk_mul_f32 v[130:131], v[96:97], 0.5 op_sel_hi:[1,0]
	v_fmamk_f32 v132, v132, 0x3a800000, v197
	v_mul_f32_e32 v133, 0x4b800000, v132
	v_cmp_gt_f32_e32 vcc, s47, v132
	s_nop 1
	v_cndmask_b32_e32 v132, v132, v133, vcc
	v_rsq_f32_e32 v134, v132
	v_pk_mul_f32 v[132:133], v[94:95], 0.5 op_sel_hi:[1,0]
	v_mul_f32_e32 v135, 0x45800000, v134
	v_cndmask_b32_e32 v182, v134, v135, vcc
	v_mov_b32_e32 v183, v182
	v_pk_mul_f32 v[134:135], v[138:139], v[182:183] op_sel_hi:[1,0]
	v_pk_mul_f32 v[136:137], v[140:141], v[182:183] op_sel_hi:[1,0]
	v_pk_mul_f32 v[134:135], v[4:5], v[134:135]
	v_pk_mul_f32 v[136:137], v[2:3], v[136:137]
	v_pk_fma_f32 v[124:125], v[130:131], v[134:135], v[124:125]
	v_pk_fma_f32 v[122:123], v[132:133], v[136:137], v[122:123]
	s_mov_b64 vcc, s[0:1]
	s_cbranch_vccz .Lrow2_448
	v_mov_b32_e32 v138, v182
	v_mov_b32_e32 v139, v182
	v_pk_mul_f32 v[132:133], v[172:173], v[138:139]
	v_pk_mul_f32 v[134:135], v[170:171], v[182:183]
	v_pk_mul_f32 v[130:131], v[100:101], 0.5 op_sel_hi:[1,0]
	v_pk_mul_f32 v[132:133], v[8:9], v[132:133]
	v_pk_mul_f32 v[134:135], v[6:7], v[134:135]
	v_pk_mul_f32 v[136:137], v[176:177], v[138:139]
	v_pk_mul_f32 v[140:141], v[174:175], v[182:183]
	v_pk_fma_f32 v[132:133], v[130:131], v[132:133], v[120:121]
	v_pk_fma_f32 v[130:131], v[188:189], v[134:135], v[118:119]
	v_pk_mul_f32 v[134:135], v[104:105], 0.5 op_sel_hi:[1,0]
	v_pk_mul_f32 v[136:137], v[20:21], v[136:137]
	v_pk_mul_f32 v[140:141], v[18:19], v[140:141]
	v_pk_mul_f32 v[138:139], v[180:181], v[138:139]
	v_pk_mul_f32 v[200:201], v[178:179], v[182:183]
	s_lshl_b64 s[0:1], s[6:7], 12
	v_pk_fma_f32 v[136:137], v[134:135], v[136:137], v[116:117]
	v_pk_fma_f32 v[134:135], v[186:187], v[140:141], v[114:115]
	v_pk_mul_f32 v[140:141], v[108:109], 0.5 op_sel_hi:[1,0]
	v_pk_mul_f32 v[138:139], v[24:25], v[138:139]
	v_pk_mul_f32 v[200:201], v[22:23], v[200:201]
	v_lshl_add_u64 v[198:199], v[160:161], 0, s[0:1]
	v_pk_fma_f32 v[140:141], v[140:141], v[138:139], v[112:113]
	v_pk_fma_f32 v[138:139], v[184:185], v[200:201], v[110:111]
	global_store_dwordx4 v[198:199], v[122:125], off
	global_store_dwordx4 v[198:199], v[130:133], off offset:1024
	global_store_dwordx4 v[198:199], v[134:137], off offset:2048
	global_store_dwordx4 v[198:199], v[138:141], off offset:3072
	s_lshl_b64 s[2:3], s[12:13], 11
	s_mov_b64 s[22:23], 0

; #define GAS __attribute__((address_space(1)))
; DI unsigned pk2(float lo, float hi) { f32x2_t v = {lo, hi}; bf16x2_t b = __builtin_convertvector(v, bf16x2_t); return __builtin_bit_cast(unsigned, b); }
; DI float bflo(unsigned w) { return __uint_as_float(w << 16); }
; DI float bfhi(unsigned w) { return __uint_as_float(w & 0xffff0000u); }
; DI void phase_e(const Ctx& C, int nslab, int has_post, int pl, int ps, float pw, int has_pre, int ql, int qs, int nrows,
;                 const GAS float* xsrc, const GAS float* csrc, GAS float* xdst, GAS float* cdst, bool xs16, bool xd16) {
;     ...
;             f32x4 y[4]; float ss = 0.f;
; #pragma unroll
;             for (int j = 0; j < 4; ++j) {
;                 if (isx || nslab == 0) { y[j] = (f32x4){bflo(yw[j].x), bfhi(yw[j].x), bflo(yw[j].y), bfhi(yw[j].y)}; }
;                 else { y[j] = (f32x4){0.f, 0.f, 0.f, 0.f};
;                     for (int s = 0; s < nslab; ++s) { const u32x2 w = *(const GAS u32x2*)(YS + ((size_t)s * MC + (row - MX)) * 1024 + 256 * j + 4 * lane); y[j] += (f32x4){bflo(w.x), bfhi(w.x), bflo(w.y), bfhi(w.y)}; } }
;                 ss += (y[j][0] * y[j][0] + y[j][1] * y[j][1]) + (y[j][2] * y[j][2] + y[j][3] * y[j][3]); }
;             const float r = rsqrtf(wave_sum(ss) * (1.0f / 1024.0f) + EPS);
;             if (isx && xd16) { GAS bf16* d16 = (GAS bf16*)xdst + (size_t)row * 1024;
; #pragma unroll
;                 for (int j = 0; j < 4; ++j) { v[j] += pw * gt[j] * ((y[j] * r) * gpo[j]); u32x2 w; w.x = pk2(v[j][0], v[j][1]); w.y = pk2(v[j][2], v[j][3]); __builtin_nontemporal_store(w, (GAS u32x2*)(d16 + 256 * j + 4 * lane));
;                     v[j] = (f32x4){bflo(w.x), bfhi(w.x), bflo(w.y), bfhi(w.y)}; }
;             } else { GAS float* dst = isx ? xdst + (size_t)row * 1024 : cdst + (size_t)(row - MX) * 1024;
; #pragma unroll
;                 for (int j = 0; j < 4; ++j) { v[j] += pw * gt[j] * ((y[j] * r) * gpo[j]); __builtin_nontemporal_store(v[j], (GAS f32x4*)(dst + 256 * j + 4 * lane)); } }
.LBB0_971:
	v_mul_f32_e32 v130, v175, v175
	v_mul_f32_e32 v131, v139, v139
	v_fmac_f32_e32 v130, v174, v174
	v_fmac_f32_e32 v131, v138, v138
	v_add_f32_e32 v130, v130, v131
	v_mul_f32_e32 v131, v171, v171
	v_mul_f32_e32 v132, v173, v173
	v_fmac_f32_e32 v131, v170, v170
	v_fmac_f32_e32 v132, v172, v172
	v_add_f32_e32 v131, v131, v132
	v_add_f32_e32 v130, v130, v131
	v_mul_f32_e32 v131, v177, v177
	v_mul_f32_e32 v132, v179, v179
	v_fmac_f32_e32 v131, v176, v176
	v_fmac_f32_e32 v132, v178, v178
	v_add_f32_e32 v131, v131, v132
	v_add_f32_e32 v136, v130, v131
	v_pk_mul_f32 v[130:131], v[182:183], v[182:183]
	v_pk_mul_f32 v[132:133], v[180:181], v[180:181]
	s_and_b64 s[0:1], exec, s[0:1]
	v_pk_mov_b32 v[134:135], v[132:133], v[130:131] op_sel:[1,0]
	v_mov_b32_e32 v133, v131
	v_pk_add_f32 v[130:131], v[134:135], v[132:133]
	s_ashr_i32 s11, s10, 31
	v_add_f32_e32 v130, v130, v131
	v_add_f32_e32 v130, v136, v130
	s_nop 1
	v_add_f32_dpp v130, v130, v130 quad_perm:[1,0,3,2] row_mask:0xf bank_mask:0xf
	s_nop 1
	v_add_f32_dpp v130, v130, v130 quad_perm:[2,3,0,1] row_mask:0xf bank_mask:0xf
	s_nop 1
	v_add_f32_dpp v130, v130, v130 row_half_mirror row_mask:0xf bank_mask:0xf
	s_nop 1
	v_add_f32_dpp v130, v130, v130 row_mirror row_mask:0xf bank_mask:0xf
	s_nop 1
	v_add_f32_dpp v130, v130, v130 row_bcast:15 row_mask:0xa bank_mask:0xf
	s_nop 1
	v_add_f32_dpp v130, v130, v130 row_bcast:31 row_mask:0xc bank_mask:0xf
	s_nop 0
	v_readlane_b32 s64, v130, 63
	s_nop 1
	v_mov_b32_e32 v130, s64
	s_waitcnt lgkmcnt(0)
	s_mov_b64 s[12:13], -1
	v_fmamk_f32 v130, v130, 0x3a800000, v192
	v_mul_f32_e32 v131, 0x4b800000, v130
	v_cmp_gt_f32_e32 vcc, s27, v130
	s_nop 1
	v_cndmask_b32_e32 v130, v130, v131, vcc
	v_rsq_f32_e32 v130, v130
	s_nop 0
	v_mul_f32_e32 v131, 0x45800000, v130
	v_cndmask_b32_e32 v184, v130, v131, vcc
	v_mov_b32_e32 v185, v184
	v_pk_mul_f32 v[130:131], v[138:139], v[184:185] op_sel_hi:[1,0]
	v_pk_mul_f32 v[134:135], v[174:175], v[184:185] op_sel_hi:[1,0]
	v_pk_mul_f32 v[130:131], v[4:5], v[130:131]
	v_pk_mul_f32 v[134:135], v[2:3], v[134:135]
	s_waitcnt vmcnt(11)
	v_pk_fma_f32 v[80:81], v[100:101], v[130:131], v[80:81]
	v_pk_fma_f32 v[78:79], v[98:99], v[134:135], v[78:79]
	s_mov_b64 vcc, s[0:1]
	s_cbranch_vccz .LBB0_973
	v_mov_b32_e32 v138, v184
	v_mov_b32_e32 v139, v184
	v_pk_mul_f32 v[130:131], v[172:173], v[138:139]
	v_pk_mul_f32 v[132:133], v[170:171], v[184:185]
	v_pk_mul_f32 v[130:131], v[8:9], v[130:131]
	v_pk_mul_f32 v[134:135], v[6:7], v[132:133]
	s_waitcnt vmcnt(7)
	v_pk_fma_f32 v[132:133], v[104:105], v[130:131], v[60:61]
	v_pk_fma_f32 v[130:131], v[102:103], v[134:135], v[58:59]
	v_pk_mul_f32 v[134:135], v[178:179], v[138:139]
	v_pk_mul_f32 v[136:137], v[176:177], v[184:185]
	v_pk_mul_f32 v[134:135], v[20:21], v[134:135]
	v_pk_mul_f32 v[140:141], v[18:19], v[136:137]
	s_waitcnt vmcnt(6)
	v_pk_fma_f32 v[136:137], v[108:109], v[134:135], v[56:57]
	v_pk_fma_f32 v[134:135], v[106:107], v[140:141], v[54:55]
	v_pk_mul_f32 v[138:139], v[182:183], v[138:139]
	v_pk_mul_f32 v[140:141], v[180:181], v[184:185]
	s_lshl_b64 s[0:1], s[4:5], 12
	v_pk_mul_f32 v[138:139], v[24:25], v[138:139]
	v_pk_mul_f32 v[194:195], v[22:23], v[140:141]
	v_lshl_add_u64 v[174:175], v[160:161], 0, s[0:1]
	s_waitcnt vmcnt(4)
	v_pk_fma_f32 v[140:141], v[112:113], v[138:139], v[48:49]
	v_pk_fma_f32 v[138:139], v[110:111], v[194:195], v[46:47]
	global_store_dwordx4 v[174:175], v[78:81], off
	global_store_dwordx4 v[174:175], v[130:133], off offset:1024
	global_store_dwordx4 v[174:175], v[134:137], off offset:2048
	global_store_dwordx4 v[174:175], v[138:141], off offset:3072
	s_lshl_b64 s[2:3], s[10:11], 11
	s_mov_b64 s[12:13], 0

; #define GAS __attribute__((address_space(1)))
; DI unsigned pk2(float lo, float hi) { f32x2_t v = {lo, hi}; bf16x2_t b = __builtin_convertvector(v, bf16x2_t); return __builtin_bit_cast(unsigned, b); }
; DI float bflo(unsigned w) { return __uint_as_float(w << 16); }
; DI float bfhi(unsigned w) { return __uint_as_float(w & 0xffff0000u); }
; DI void phase_e(const Ctx& C, int nslab, int has_post, int pl, int ps, float pw, int has_pre, int ql, int qs, int nrows,
;                 const GAS float* xsrc, const GAS float* csrc, GAS float* xdst, GAS float* cdst, bool xs16, bool xd16) {
;     ...
;             f32x4 y[4]; float ss = 0.f;
; #pragma unroll
;             for (int j = 0; j < 4; ++j) {
;                 if (isx || nslab == 0) { y[j] = (f32x4){bflo(yw[j].x), bfhi(yw[j].x), bflo(yw[j].y), bfhi(yw[j].y)}; }
;                 else { y[j] = (f32x4){0.f, 0.f, 0.f, 0.f};
;                     for (int s = 0; s < nslab; ++s) { const u32x2 w = *(const GAS u32x2*)(YS + ((size_t)s * MC + (row - MX)) * 1024 + 256 * j + 4 * lane); y[j] += (f32x4){bflo(w.x), bfhi(w.x), bflo(w.y), bfhi(w.y)}; } }
;                 ss += (y[j][0] * y[j][0] + y[j][1] * y[j][1]) + (y[j][2] * y[j][2] + y[j][3] * y[j][3]); }
;             const float r = rsqrtf(wave_sum(ss) * (1.0f / 1024.0f) + EPS);
;             if (isx && xd16) { GAS bf16* d16 = (GAS bf16*)xdst + (size_t)row * 1024;
; #pragma unroll
;                 for (int j = 0; j < 4; ++j) { v[j] += pw * gt[j] * ((y[j] * r) * gpo[j]); u32x2 w; w.x = pk2(v[j][0], v[j][1]); w.y = pk2(v[j][2], v[j][3]); __builtin_nontemporal_store(w, (GAS u32x2*)(d16 + 256 * j + 4 * lane));
;                     v[j] = (f32x4){bflo(w.x), bfhi(w.x), bflo(w.y), bfhi(w.y)}; }
;             } else { GAS float* dst = isx ? xdst + (size_t)row * 1024 : cdst + (size_t)(row - MX) * 1024;
; #pragma unroll
;                 for (int j = 0; j < 4; ++j) { v[j] += pw * gt[j] * ((y[j] * r) * gpo[j]); __builtin_nontemporal_store(v[j], (GAS f32x4*)(dst + 256 * j + 4 * lane)); } }
.Lrow1_971:
	v_mul_f32_e32 v130, v175, v175
	v_mul_f32_e32 v131, v139, v139
	v_fmac_f32_e32 v130, v174, v174
	v_fmac_f32_e32 v131, v138, v138
	v_add_f32_e32 v130, v130, v131
	v_mul_f32_e32 v131, v171, v171
	v_mul_f32_e32 v132, v173, v173
	v_fmac_f32_e32 v131, v170, v170
	v_fmac_f32_e32 v132, v172, v172
	v_add_f32_e32 v131, v131, v132
	v_add_f32_e32 v130, v130, v131
	v_mul_f32_e32 v131, v177, v177
	v_mul_f32_e32 v132, v179, v179
	v_fmac_f32_e32 v131, v176, v176
	v_fmac_f32_e32 v132, v178, v178
	v_add_f32_e32 v131, v131, v132
	v_add_f32_e32 v136, v130, v131
	v_pk_mul_f32 v[130:131], v[182:183], v[182:183]
	v_pk_mul_f32 v[132:133], v[180:181], v[180:181]
	s_and_b64 s[0:1], exec, s[0:1]
	v_pk_mov_b32 v[134:135], v[132:133], v[130:131] op_sel:[1,0]
	v_mov_b32_e32 v133, v131
	v_pk_add_f32 v[130:131], v[134:135], v[132:133]
	s_ashr_i32 s11, s10, 31
	v_add_f32_e32 v130, v130, v131
	v_add_f32_e32 v130, v136, v130
	s_nop 1
	v_add_f32_dpp v130, v130, v130 quad_perm:[1,0,3,2] row_mask:0xf bank_mask:0xf
	s_nop 1
	v_add_f32_dpp v130, v130, v130 quad_perm:[2,3,0,1] row_mask:0xf bank_mask:0xf
	s_nop 1
	v_add_f32_dpp v130, v130, v130 row_half_mirror row_mask:0xf bank_mask:0xf
	s_nop 1
	v_add_f32_dpp v130, v130, v130 row_mirror row_mask:0xf bank_mask:0xf
	s_nop 1
	v_add_f32_dpp v130, v130, v130 row_bcast:15 row_mask:0xa bank_mask:0xf
	s_nop 1
	v_add_f32_dpp v130, v130, v130 row_bcast:31 row_mask:0xc bank_mask:0xf
	s_nop 0
	v_readlane_b32 s64, v130, 63
	s_nop 1
	v_mov_b32_e32 v130, s64
	s_waitcnt lgkmcnt(0)
	s_mov_b64 s[12:13], -1
	v_fmamk_f32 v130, v130, 0x3a800000, v192
	v_mul_f32_e32 v131, 0x4b800000, v130
	v_cmp_gt_f32_e32 vcc, s27, v130
	s_nop 1
	v_cndmask_b32_e32 v130, v130, v131, vcc
	v_rsq_f32_e32 v130, v130
	s_nop 0
	v_mul_f32_e32 v131, 0x45800000, v130
	v_cndmask_b32_e32 v184, v130, v131, vcc
	v_mov_b32_e32 v185, v184
	v_pk_mul_f32 v[130:131], v[138:139], v[184:185] op_sel_hi:[1,0]
	v_pk_mul_f32 v[134:135], v[174:175], v[184:185] op_sel_hi:[1,0]
	v_pk_mul_f32 v[130:131], v[4:5], v[130:131]
	v_pk_mul_f32 v[134:135], v[2:3], v[134:135]
	s_waitcnt vmcnt(11)
	v_pk_fma_f32 v[36:37], v[100:101], v[130:131], v[36:37]
	v_pk_fma_f32 v[34:35], v[98:99], v[134:135], v[34:35]
	s_mov_b64 vcc, s[0:1]
	s_cbranch_vccz .Lrow1_973
	v_mov_b32_e32 v138, v184
	v_mov_b32_e32 v139, v184
	v_pk_mul_f32 v[130:131], v[172:173], v[138:139]
	v_pk_mul_f32 v[132:133], v[170:171], v[184:185]
	v_pk_mul_f32 v[130:131], v[8:9], v[130:131]
	v_pk_mul_f32 v[134:135], v[6:7], v[132:133]
	s_waitcnt vmcnt(7)
	v_pk_fma_f32 v[132:133], v[104:105], v[130:131], v[40:41]
	v_pk_fma_f32 v[130:131], v[102:103], v[134:135], v[38:39]
	v_pk_mul_f32 v[134:135], v[178:179], v[138:139]
	v_pk_mul_f32 v[136:137], v[176:177], v[184:185]
	v_pk_mul_f32 v[134:135], v[20:21], v[134:135]
	v_pk_mul_f32 v[140:141], v[18:19], v[136:137]
	s_waitcnt vmcnt(6)
	v_pk_fma_f32 v[136:137], v[108:109], v[134:135], v[44:45]
	v_pk_fma_f32 v[134:135], v[106:107], v[140:141], v[42:43]
	v_pk_mul_f32 v[138:139], v[182:183], v[138:139]
	v_pk_mul_f32 v[140:141], v[180:181], v[184:185]
	s_lshl_b64 s[0:1], s[4:5], 12
	v_pk_mul_f32 v[138:139], v[24:25], v[138:139]
	v_pk_mul_f32 v[194:195], v[22:23], v[140:141]
	v_lshl_add_u64 v[174:175], v[160:161], 0, s[0:1]
	s_waitcnt vmcnt(4)
	v_pk_fma_f32 v[140:141], v[112:113], v[138:139], v[52:53]
	v_pk_fma_f32 v[138:139], v[110:111], v[194:195], v[50:51]
	global_store_dwordx4 v[174:175], v[34:37], off
	global_store_dwordx4 v[174:175], v[130:133], off offset:1024
	global_store_dwordx4 v[174:175], v[134:137], off offset:2048
	global_store_dwordx4 v[174:175], v[138:141], off offset:3072
	s_lshl_b64 s[2:3], s[10:11], 11
	s_mov_b64 s[12:13], 0

; #define GAS __attribute__((address_space(1)))
; DI unsigned pk2(float lo, float hi) { f32x2_t v = {lo, hi}; bf16x2_t b = __builtin_convertvector(v, bf16x2_t); return __builtin_bit_cast(unsigned, b); }
; DI float bflo(unsigned w) { return __uint_as_float(w << 16); }
; DI float bfhi(unsigned w) { return __uint_as_float(w & 0xffff0000u); }
; DI void phase_e(const Ctx& C, int nslab, int has_post, int pl, int ps, float pw, int has_pre, int ql, int qs, int nrows,
;                 const GAS float* xsrc, const GAS float* csrc, GAS float* xdst, GAS float* cdst, bool xs16, bool xd16) {
;     ...
;             f32x4 y[4]; float ss = 0.f;
; #pragma unroll
;             for (int j = 0; j < 4; ++j) {
;                 if (isx || nslab == 0) { y[j] = (f32x4){bflo(yw[j].x), bfhi(yw[j].x), bflo(yw[j].y), bfhi(yw[j].y)}; }
;                 else { y[j] = (f32x4){0.f, 0.f, 0.f, 0.f};
;                     for (int s = 0; s < nslab; ++s) { const u32x2 w = *(const GAS u32x2*)(YS + ((size_t)s * MC + (row - MX)) * 1024 + 256 * j + 4 * lane); y[j] += (f32x4){bflo(w.x), bfhi(w.x), bflo(w.y), bfhi(w.y)}; } }
;                 ss += (y[j][0] * y[j][0] + y[j][1] * y[j][1]) + (y[j][2] * y[j][2] + y[j][3] * y[j][3]); }
;             const float r = rsqrtf(wave_sum(ss) * (1.0f / 1024.0f) + EPS);
;             if (isx && xd16) { GAS bf16* d16 = (GAS bf16*)xdst + (size_t)row * 1024;
; #pragma unroll
;                 for (int j = 0; j < 4; ++j) { v[j] += pw * gt[j] * ((y[j] * r) * gpo[j]); u32x2 w; w.x = pk2(v[j][0], v[j][1]); w.y = pk2(v[j][2], v[j][3]); __builtin_nontemporal_store(w, (GAS u32x2*)(d16 + 256 * j + 4 * lane));
;                     v[j] = (f32x4){bflo(w.x), bfhi(w.x), bflo(w.y), bfhi(w.y)}; }
;             } else { GAS float* dst = isx ? xdst + (size_t)row * 1024 : cdst + (size_t)(row - MX) * 1024;
; #pragma unroll
;                 for (int j = 0; j < 4; ++j) { v[j] += pw * gt[j] * ((y[j] * r) * gpo[j]); __builtin_nontemporal_store(v[j], (GAS f32x4*)(dst + 256 * j + 4 * lane)); } }
.Lrow2_971:
	v_mul_f32_e32 v130, v175, v175
	v_mul_f32_e32 v131, v139, v139
	v_fmac_f32_e32 v130, v174, v174
	v_fmac_f32_e32 v131, v138, v138
	v_add_f32_e32 v130, v130, v131
	v_mul_f32_e32 v131, v171, v171
	v_mul_f32_e32 v132, v173, v173
	v_fmac_f32_e32 v131, v170, v170
	v_fmac_f32_e32 v132, v172, v172
	v_add_f32_e32 v131, v131, v132
	v_add_f32_e32 v130, v130, v131
	v_mul_f32_e32 v131, v177, v177
	v_mul_f32_e32 v132, v179, v179
	v_fmac_f32_e32 v131, v176, v176
	v_fmac_f32_e32 v132, v178, v178
	v_add_f32_e32 v131, v131, v132
	v_add_f32_e32 v136, v130, v131
	v_pk_mul_f32 v[130:131], v[182:183], v[182:183]
	v_pk_mul_f32 v[132:133], v[180:181], v[180:181]
	s_and_b64 s[0:1], exec, s[0:1]
	v_pk_mov_b32 v[134:135], v[132:133], v[130:131] op_sel:[1,0]
	v_mov_b32_e32 v133, v131
	v_pk_add_f32 v[130:131], v[134:135], v[132:133]
	s_ashr_i32 s11, s10, 31
	v_add_f32_e32 v130, v130, v131
	v_add_f32_e32 v130, v136, v130
	s_nop 1
	v_add_f32_dpp v130, v130, v130 quad_perm:[1,0,3,2] row_mask:0xf bank_mask:0xf
	s_nop 1
	v_add_f32_dpp v130, v130, v130 quad_perm:[2,3,0,1] row_mask:0xf bank_mask:0xf
	s_nop 1
	v_add_f32_dpp v130, v130, v130 row_half_mirror row_mask:0xf bank_mask:0xf
	s_nop 1
	v_add_f32_dpp v130, v130, v130 row_mirror row_mask:0xf bank_mask:0xf
	s_nop 1
	v_add_f32_dpp v130, v130, v130 row_bcast:15 row_mask:0xa bank_mask:0xf
	s_nop 1
	v_add_f32_dpp v130, v130, v130 row_bcast:31 row_mask:0xc bank_mask:0xf
	s_nop 0
	v_readlane_b32 s64, v130, 63
	s_nop 1
	v_mov_b32_e32 v130, s64
	s_waitcnt lgkmcnt(0)
	s_mov_b64 s[12:13], -1
	v_fmamk_f32 v130, v130, 0x3a800000, v192
	v_mul_f32_e32 v131, 0x4b800000, v130
	v_cmp_gt_f32_e32 vcc, s27, v130
	s_nop 1
	v_cndmask_b32_e32 v130, v130, v131, vcc
	v_rsq_f32_e32 v130, v130
	s_nop 0
	v_mul_f32_e32 v131, 0x45800000, v130
	v_cndmask_b32_e32 v184, v130, v131, vcc
	v_mov_b32_e32 v185, v184
	v_pk_mul_f32 v[130:131], v[138:139], v[184:185] op_sel_hi:[1,0]
	v_pk_mul_f32 v[134:135], v[174:175], v[184:185] op_sel_hi:[1,0]
	v_pk_mul_f32 v[130:131], v[4:5], v[130:131]
	v_pk_mul_f32 v[134:135], v[2:3], v[134:135]
	s_waitcnt vmcnt(11)
	v_pk_fma_f32 v[116:117], v[100:101], v[130:131], v[116:117]
	v_pk_fma_f32 v[114:115], v[98:99], v[134:135], v[114:115]
	s_mov_b64 vcc, s[0:1]
	s_cbranch_vccz .Lrow2_973
	v_mov_b32_e32 v138, v184
	v_mov_b32_e32 v139, v184
	v_pk_mul_f32 v[130:131], v[172:173], v[138:139]
	v_pk_mul_f32 v[132:133], v[170:171], v[184:185]
	v_pk_mul_f32 v[130:131], v[8:9], v[130:131]
	v_pk_mul_f32 v[134:135], v[6:7], v[132:133]
	s_waitcnt vmcnt(7)
	v_pk_fma_f32 v[132:133], v[104:105], v[130:131], v[120:121]
	v_pk_fma_f32 v[130:131], v[102:103], v[134:135], v[118:119]
	v_pk_mul_f32 v[134:135], v[178:179], v[138:139]
	v_pk_mul_f32 v[136:137], v[176:177], v[184:185]
	v_pk_mul_f32 v[134:135], v[20:21], v[134:135]
	v_pk_mul_f32 v[140:141], v[18:19], v[136:137]
	s_waitcnt vmcnt(6)
	v_pk_fma_f32 v[136:137], v[108:109], v[134:135], v[124:125]
	v_pk_fma_f32 v[134:135], v[106:107], v[140:141], v[122:123]
	v_pk_mul_f32 v[138:139], v[182:183], v[138:139]
	v_pk_mul_f32 v[140:141], v[180:181], v[184:185]
	s_lshl_b64 s[0:1], s[4:5], 12
	v_pk_mul_f32 v[138:139], v[24:25], v[138:139]
	v_pk_mul_f32 v[194:195], v[22:23], v[140:141]
	v_lshl_add_u64 v[174:175], v[160:161], 0, s[0:1]
	s_waitcnt vmcnt(4)
	v_pk_fma_f32 v[140:141], v[112:113], v[138:139], v[128:129]
	v_pk_fma_f32 v[138:139], v[110:111], v[194:195], v[126:127]
	global_store_dwordx4 v[174:175], v[114:117], off
	global_store_dwordx4 v[174:175], v[130:133], off offset:1024
	global_store_dwordx4 v[174:175], v[134:137], off offset:2048
	global_store_dwordx4 v[174:175], v[138:141], off offset:3072
	s_lshl_b64 s[2:3], s[10:11], 11
	s_mov_b64 s[12:13], 0

; #define GAS __attribute__((address_space(1)))
; DI unsigned pk2(float lo, float hi) { f32x2_t v = {lo, hi}; bf16x2_t b = __builtin_convertvector(v, bf16x2_t); return __builtin_bit_cast(unsigned, b); }
; DI float bflo(unsigned w) { return __uint_as_float(w << 16); }
; DI float bfhi(unsigned w) { return __uint_as_float(w & 0xffff0000u); }
; DI void phase_e(const Ctx& C, int nslab, int has_post, int pl, int ps, float pw, int has_pre, int ql, int qs, int nrows,
;                 const GAS float* xsrc, const GAS float* csrc, GAS float* xdst, GAS float* cdst, bool xs16, bool xd16) {
;     ...
;             f32x4 y[4]; float ss = 0.f;
; #pragma unroll
;             for (int j = 0; j < 4; ++j) {
;                 if (isx || nslab == 0) { y[j] = (f32x4){bflo(yw[j].x), bfhi(yw[j].x), bflo(yw[j].y), bfhi(yw[j].y)}; }
;                 else { y[j] = (f32x4){0.f, 0.f, 0.f, 0.f};
;                     for (int s = 0; s < nslab; ++s) { const u32x2 w = *(const GAS u32x2*)(YS + ((size_t)s * MC + (row - MX)) * 1024 + 256 * j + 4 * lane); y[j] += (f32x4){bflo(w.x), bfhi(w.x), bflo(w.y), bfhi(w.y)}; } }
;                 ss += (y[j][0] * y[j][0] + y[j][1] * y[j][1]) + (y[j][2] * y[j][2] + y[j][3] * y[j][3]); }
;             const float r = rsqrtf(wave_sum(ss) * (1.0f / 1024.0f) + EPS);
;             if (isx && xd16) { GAS bf16* d16 = (GAS bf16*)xdst + (size_t)row * 1024;
; #pragma unroll
;                 for (int j = 0; j < 4; ++j) { v[j] += pw * gt[j] * ((y[j] * r) * gpo[j]); u32x2 w; w.x = pk2(v[j][0], v[j][1]); w.y = pk2(v[j][2], v[j][3]); __builtin_nontemporal_store(w, (GAS u32x2*)(d16 + 256 * j + 4 * lane));
;                     v[j] = (f32x4){bflo(w.x), bfhi(w.x), bflo(w.y), bfhi(w.y)}; }
;             } else { GAS float* dst = isx ? xdst + (size_t)row * 1024 : cdst + (size_t)(row - MX) * 1024;
; #pragma unroll
;                 for (int j = 0; j < 4; ++j) { v[j] += pw * gt[j] * ((y[j] * r) * gpo[j]); __builtin_nontemporal_store(v[j], (GAS f32x4*)(dst + 256 * j + 4 * lane)); } }
.LBB0_1238:
	v_mul_f32_e32 v130, v141, v141
	v_mul_f32_e32 v131, v139, v139
	v_fmac_f32_e32 v130, v140, v140
	v_fmac_f32_e32 v131, v138, v138
	v_add_f32_e32 v130, v130, v131
	v_mul_f32_e32 v131, v171, v171
	v_mul_f32_e32 v132, v173, v173
	v_fmac_f32_e32 v131, v170, v170
	v_fmac_f32_e32 v132, v172, v172
	v_add_f32_e32 v131, v131, v132
	v_add_f32_e32 v130, v130, v131
	v_mul_f32_e32 v131, v175, v175
	v_mul_f32_e32 v132, v177, v177
	v_fmac_f32_e32 v131, v174, v174
	v_fmac_f32_e32 v132, v176, v176
	v_add_f32_e32 v131, v131, v132
	v_add_f32_e32 v136, v130, v131
	v_pk_mul_f32 v[130:131], v[180:181], v[180:181]
	v_pk_mul_f32 v[132:133], v[178:179], v[178:179]
	s_and_b64 s[0:1], exec, s[0:1]
	v_pk_mov_b32 v[134:135], v[132:133], v[130:131] op_sel:[1,0]
	v_mov_b32_e32 v133, v131
	v_pk_add_f32 v[130:131], v[134:135], v[132:133]
	s_ashr_i32 s11, s10, 31
	v_add_f32_e32 v130, v130, v131
	v_add_f32_e32 v130, v136, v130
	s_nop 1
	v_add_f32_dpp v130, v130, v130 quad_perm:[1,0,3,2] row_mask:0xf bank_mask:0xf
	s_nop 1
	v_add_f32_dpp v130, v130, v130 quad_perm:[2,3,0,1] row_mask:0xf bank_mask:0xf
	s_nop 1
	v_add_f32_dpp v130, v130, v130 row_half_mirror row_mask:0xf bank_mask:0xf
	s_nop 1
	v_add_f32_dpp v130, v130, v130 row_mirror row_mask:0xf bank_mask:0xf
	s_nop 1
	v_add_f32_dpp v130, v130, v130 row_bcast:15 row_mask:0xa bank_mask:0xf
	s_nop 1
	v_add_f32_dpp v130, v130, v130 row_bcast:31 row_mask:0xc bank_mask:0xf
	s_nop 0
	v_readlane_b32 s64, v130, 63
	s_nop 1
	v_mov_b32_e32 v132, s64
	s_waitcnt lgkmcnt(0)
	s_mov_b64 s[12:13], -1
	s_waitcnt vmcnt(7)
	v_pk_mul_f32 v[188:189], v[102:103], 0.5 op_sel_hi:[1,0]
	s_waitcnt vmcnt(6)
	v_pk_mul_f32 v[186:187], v[106:107], 0.5 op_sel_hi:[1,0]
	s_waitcnt vmcnt(4)
	v_pk_mul_f32 v[184:185], v[110:111], 0.5 op_sel_hi:[1,0]
	v_pk_mul_f32 v[130:131], v[96:97], 0.5 op_sel_hi:[1,0]
	v_fmamk_f32 v132, v132, 0x3a800000, v196
	v_mul_f32_e32 v133, 0x4b800000, v132
	v_cmp_gt_f32_e32 vcc, s25, v132
	s_nop 1
	v_cndmask_b32_e32 v132, v132, v133, vcc
	v_rsq_f32_e32 v134, v132
	v_pk_mul_f32 v[132:133], v[94:95], 0.5 op_sel_hi:[1,0]
	v_mul_f32_e32 v135, 0x45800000, v134
	v_cndmask_b32_e32 v182, v134, v135, vcc
	v_mov_b32_e32 v183, v182
	v_pk_mul_f32 v[134:135], v[138:139], v[182:183] op_sel_hi:[1,0]
	v_pk_mul_f32 v[136:137], v[140:141], v[182:183] op_sel_hi:[1,0]
	v_pk_mul_f32 v[134:135], v[4:5], v[134:135]
	v_pk_mul_f32 v[136:137], v[2:3], v[136:137]
	v_pk_fma_f32 v[100:101], v[130:131], v[134:135], v[100:101]
	v_pk_fma_f32 v[98:99], v[132:133], v[136:137], v[98:99]
	s_mov_b64 vcc, s[0:1]
	s_cbranch_vccz .LBB0_1240
	v_mov_b32_e32 v138, v182
	v_mov_b32_e32 v139, v182
	v_pk_mul_f32 v[132:133], v[172:173], v[138:139]
	v_pk_mul_f32 v[134:135], v[170:171], v[182:183]
	v_pk_mul_f32 v[130:131], v[104:105], 0.5 op_sel_hi:[1,0]
	v_pk_mul_f32 v[132:133], v[8:9], v[132:133]
	v_pk_mul_f32 v[134:135], v[6:7], v[134:135]
	v_pk_mul_f32 v[136:137], v[176:177], v[138:139]
	v_pk_mul_f32 v[140:141], v[174:175], v[182:183]
	v_pk_fma_f32 v[132:133], v[130:131], v[132:133], v[60:61]
	v_pk_fma_f32 v[130:131], v[188:189], v[134:135], v[58:59]
	v_pk_mul_f32 v[134:135], v[108:109], 0.5 op_sel_hi:[1,0]
	v_pk_mul_f32 v[136:137], v[20:21], v[136:137]
	v_pk_mul_f32 v[140:141], v[18:19], v[140:141]
	v_pk_mul_f32 v[138:139], v[180:181], v[138:139]
	v_pk_mul_f32 v[200:201], v[178:179], v[182:183]
	s_lshl_b64 s[0:1], s[4:5], 12
	v_pk_fma_f32 v[136:137], v[134:135], v[136:137], v[56:57]
	v_pk_fma_f32 v[134:135], v[186:187], v[140:141], v[54:55]
	v_pk_mul_f32 v[140:141], v[112:113], 0.5 op_sel_hi:[1,0]
	v_pk_mul_f32 v[138:139], v[24:25], v[138:139]
	v_pk_mul_f32 v[200:201], v[22:23], v[200:201]
	v_lshl_add_u64 v[198:199], v[160:161], 0, s[0:1]
	v_pk_fma_f32 v[140:141], v[140:141], v[138:139], v[48:49]
	v_pk_fma_f32 v[138:139], v[184:185], v[200:201], v[46:47]
	global_store_dwordx4 v[198:199], v[98:101], off
	global_store_dwordx4 v[198:199], v[130:133], off offset:1024
	global_store_dwordx4 v[198:199], v[134:137], off offset:2048
	global_store_dwordx4 v[198:199], v[138:141], off offset:3072
	s_lshl_b64 s[2:3], s[10:11], 11
	s_mov_b64 s[12:13], 0

; #define GAS __attribute__((address_space(1)))
; DI unsigned pk2(float lo, float hi) { f32x2_t v = {lo, hi}; bf16x2_t b = __builtin_convertvector(v, bf16x2_t); return __builtin_bit_cast(unsigned, b); }
; DI float bflo(unsigned w) { return __uint_as_float(w << 16); }
; DI float bfhi(unsigned w) { return __uint_as_float(w & 0xffff0000u); }
; DI void phase_e(const Ctx& C, int nslab, int has_post, int pl, int ps, float pw, int has_pre, int ql, int qs, int nrows,
;                 const GAS float* xsrc, const GAS float* csrc, GAS float* xdst, GAS float* cdst, bool xs16, bool xd16) {
;     ...
;             f32x4 y[4]; float ss = 0.f;
; #pragma unroll
;             for (int j = 0; j < 4; ++j) {
;                 if (isx || nslab == 0) { y[j] = (f32x4){bflo(yw[j].x), bfhi(yw[j].x), bflo(yw[j].y), bfhi(yw[j].y)}; }
;                 else { y[j] = (f32x4){0.f, 0.f, 0.f, 0.f};
;                     for (int s = 0; s < nslab; ++s) { const u32x2 w = *(const GAS u32x2*)(YS + ((size_t)s * MC + (row - MX)) * 1024 + 256 * j + 4 * lane); y[j] += (f32x4){bflo(w.x), bfhi(w.x), bflo(w.y), bfhi(w.y)}; } }
;                 ss += (y[j][0] * y[j][0] + y[j][1] * y[j][1]) + (y[j][2] * y[j][2] + y[j][3] * y[j][3]); }
;             const float r = rsqrtf(wave_sum(ss) * (1.0f / 1024.0f) + EPS);
;             if (isx && xd16) { GAS bf16* d16 = (GAS bf16*)xdst + (size_t)row * 1024;
; #pragma unroll
;                 for (int j = 0; j < 4; ++j) { v[j] += pw * gt[j] * ((y[j] * r) * gpo[j]); u32x2 w; w.x = pk2(v[j][0], v[j][1]); w.y = pk2(v[j][2], v[j][3]); __builtin_nontemporal_store(w, (GAS u32x2*)(d16 + 256 * j + 4 * lane));
;                     v[j] = (f32x4){bflo(w.x), bfhi(w.x), bflo(w.y), bfhi(w.y)}; }
;             } else { GAS float* dst = isx ? xdst + (size_t)row * 1024 : cdst + (size_t)(row - MX) * 1024;
; #pragma unroll
;                 for (int j = 0; j < 4; ++j) { v[j] += pw * gt[j] * ((y[j] * r) * gpo[j]); __builtin_nontemporal_store(v[j], (GAS f32x4*)(dst + 256 * j + 4 * lane)); } }
.Lrow1_1238:
	v_mul_f32_e32 v130, v141, v141
	v_mul_f32_e32 v131, v139, v139
	v_fmac_f32_e32 v130, v140, v140
	v_fmac_f32_e32 v131, v138, v138
	v_add_f32_e32 v130, v130, v131
	v_mul_f32_e32 v131, v171, v171
	v_mul_f32_e32 v132, v173, v173
	v_fmac_f32_e32 v131, v170, v170
	v_fmac_f32_e32 v132, v172, v172
	v_add_f32_e32 v131, v131, v132
	v_add_f32_e32 v130, v130, v131
	v_mul_f32_e32 v131, v175, v175
	v_mul_f32_e32 v132, v177, v177
	v_fmac_f32_e32 v131, v174, v174
	v_fmac_f32_e32 v132, v176, v176
	v_add_f32_e32 v131, v131, v132
	v_add_f32_e32 v136, v130, v131
	v_pk_mul_f32 v[130:131], v[180:181], v[180:181]
	v_pk_mul_f32 v[132:133], v[178:179], v[178:179]
	s_and_b64 s[0:1], exec, s[0:1]
	v_pk_mov_b32 v[134:135], v[132:133], v[130:131] op_sel:[1,0]
	v_mov_b32_e32 v133, v131
	v_pk_add_f32 v[130:131], v[134:135], v[132:133]
	s_ashr_i32 s11, s10, 31
	v_add_f32_e32 v130, v130, v131
	v_add_f32_e32 v130, v136, v130
	s_nop 1
	v_add_f32_dpp v130, v130, v130 quad_perm:[1,0,3,2] row_mask:0xf bank_mask:0xf
	s_nop 1
	v_add_f32_dpp v130, v130, v130 quad_perm:[2,3,0,1] row_mask:0xf bank_mask:0xf
	s_nop 1
	v_add_f32_dpp v130, v130, v130 row_half_mirror row_mask:0xf bank_mask:0xf
	s_nop 1
	v_add_f32_dpp v130, v130, v130 row_mirror row_mask:0xf bank_mask:0xf
	s_nop 1
	v_add_f32_dpp v130, v130, v130 row_bcast:15 row_mask:0xa bank_mask:0xf
	s_nop 1
	v_add_f32_dpp v130, v130, v130 row_bcast:31 row_mask:0xc bank_mask:0xf
	s_nop 0
	v_readlane_b32 s64, v130, 63
	s_nop 1
	v_mov_b32_e32 v132, s64
	s_waitcnt lgkmcnt(0)
	s_mov_b64 s[12:13], -1
	s_waitcnt vmcnt(7)
	v_pk_mul_f32 v[188:189], v[102:103], 0.5 op_sel_hi:[1,0]
	s_waitcnt vmcnt(6)
	v_pk_mul_f32 v[186:187], v[106:107], 0.5 op_sel_hi:[1,0]
	s_waitcnt vmcnt(4)
	v_pk_mul_f32 v[184:185], v[110:111], 0.5 op_sel_hi:[1,0]
	v_pk_mul_f32 v[130:131], v[96:97], 0.5 op_sel_hi:[1,0]
	v_fmamk_f32 v132, v132, 0x3a800000, v196
	v_mul_f32_e32 v133, 0x4b800000, v132
	v_cmp_gt_f32_e32 vcc, s25, v132
	s_nop 1
	v_cndmask_b32_e32 v132, v132, v133, vcc
	v_rsq_f32_e32 v134, v132
	v_pk_mul_f32 v[132:133], v[94:95], 0.5 op_sel_hi:[1,0]
	v_mul_f32_e32 v135, 0x45800000, v134
	v_cndmask_b32_e32 v182, v134, v135, vcc
	v_mov_b32_e32 v183, v182
	v_pk_mul_f32 v[134:135], v[138:139], v[182:183] op_sel_hi:[1,0]
	v_pk_mul_f32 v[136:137], v[140:141], v[182:183] op_sel_hi:[1,0]
	v_pk_mul_f32 v[134:135], v[4:5], v[134:135]
	v_pk_mul_f32 v[136:137], v[2:3], v[136:137]
	v_pk_fma_f32 v[36:37], v[130:131], v[134:135], v[36:37]
	v_pk_fma_f32 v[34:35], v[132:133], v[136:137], v[34:35]
	s_mov_b64 vcc, s[0:1]
	s_cbranch_vccz .Lrow1_1240
	v_mov_b32_e32 v138, v182
	v_mov_b32_e32 v139, v182
	v_pk_mul_f32 v[132:133], v[172:173], v[138:139]
	v_pk_mul_f32 v[134:135], v[170:171], v[182:183]
	v_pk_mul_f32 v[130:131], v[104:105], 0.5 op_sel_hi:[1,0]
	v_pk_mul_f32 v[132:133], v[8:9], v[132:133]
	v_pk_mul_f32 v[134:135], v[6:7], v[134:135]
	v_pk_mul_f32 v[136:137], v[176:177], v[138:139]
	v_pk_mul_f32 v[140:141], v[174:175], v[182:183]
	v_pk_fma_f32 v[132:133], v[130:131], v[132:133], v[40:41]
	v_pk_fma_f32 v[130:131], v[188:189], v[134:135], v[38:39]
	v_pk_mul_f32 v[134:135], v[108:109], 0.5 op_sel_hi:[1,0]
	v_pk_mul_f32 v[136:137], v[20:21], v[136:137]
	v_pk_mul_f32 v[140:141], v[18:19], v[140:141]
	v_pk_mul_f32 v[138:139], v[180:181], v[138:139]
	v_pk_mul_f32 v[200:201], v[178:179], v[182:183]
	s_lshl_b64 s[0:1], s[4:5], 12
	v_pk_fma_f32 v[136:137], v[134:135], v[136:137], v[44:45]
	v_pk_fma_f32 v[134:135], v[186:187], v[140:141], v[42:43]
	v_pk_mul_f32 v[140:141], v[112:113], 0.5 op_sel_hi:[1,0]
	v_pk_mul_f32 v[138:139], v[24:25], v[138:139]
	v_pk_mul_f32 v[200:201], v[22:23], v[200:201]
	v_lshl_add_u64 v[198:199], v[160:161], 0, s[0:1]
	v_pk_fma_f32 v[140:141], v[140:141], v[138:139], v[52:53]
	v_pk_fma_f32 v[138:139], v[184:185], v[200:201], v[50:51]
	global_store_dwordx4 v[198:199], v[34:37], off
	global_store_dwordx4 v[198:199], v[130:133], off offset:1024
	global_store_dwordx4 v[198:199], v[134:137], off offset:2048
	global_store_dwordx4 v[198:199], v[138:141], off offset:3072
	s_lshl_b64 s[2:3], s[10:11], 11
	s_mov_b64 s[12:13], 0

; #define GAS __attribute__((address_space(1)))
; DI unsigned pk2(float lo, float hi) { f32x2_t v = {lo, hi}; bf16x2_t b = __builtin_convertvector(v, bf16x2_t); return __builtin_bit_cast(unsigned, b); }
; DI float bflo(unsigned w) { return __uint_as_float(w << 16); }
; DI float bfhi(unsigned w) { return __uint_as_float(w & 0xffff0000u); }
; DI void phase_e(const Ctx& C, int nslab, int has_post, int pl, int ps, float pw, int has_pre, int ql, int qs, int nrows,
;                 const GAS float* xsrc, const GAS float* csrc, GAS float* xdst, GAS float* cdst, bool xs16, bool xd16) {
;     ...
;             f32x4 y[4]; float ss = 0.f;
; #pragma unroll
;             for (int j = 0; j < 4; ++j) {
;                 if (isx || nslab == 0) { y[j] = (f32x4){bflo(yw[j].x), bfhi(yw[j].x), bflo(yw[j].y), bfhi(yw[j].y)}; }
;                 else { y[j] = (f32x4){0.f, 0.f, 0.f, 0.f};
;                     for (int s = 0; s < nslab; ++s) { const u32x2 w = *(const GAS u32x2*)(YS + ((size_t)s * MC + (row - MX)) * 1024 + 256 * j + 4 * lane); y[j] += (f32x4){bflo(w.x), bfhi(w.x), bflo(w.y), bfhi(w.y)}; } }
;                 ss += (y[j][0] * y[j][0] + y[j][1] * y[j][1]) + (y[j][2] * y[j][2] + y[j][3] * y[j][3]); }
;             const float r = rsqrtf(wave_sum(ss) * (1.0f / 1024.0f) + EPS);
;             if (isx && xd16) { GAS bf16* d16 = (GAS bf16*)xdst + (size_t)row * 1024;
; #pragma unroll
;                 for (int j = 0; j < 4; ++j) { v[j] += pw * gt[j] * ((y[j] * r) * gpo[j]); u32x2 w; w.x = pk2(v[j][0], v[j][1]); w.y = pk2(v[j][2], v[j][3]); __builtin_nontemporal_store(w, (GAS u32x2*)(d16 + 256 * j + 4 * lane));
;                     v[j] = (f32x4){bflo(w.x), bfhi(w.x), bflo(w.y), bfhi(w.y)}; }
;             } else { GAS float* dst = isx ? xdst + (size_t)row * 1024 : cdst + (size_t)(row - MX) * 1024;
; #pragma unroll
;                 for (int j = 0; j < 4; ++j) { v[j] += pw * gt[j] * ((y[j] * r) * gpo[j]); __builtin_nontemporal_store(v[j], (GAS f32x4*)(dst + 256 * j + 4 * lane)); } }
.Lrow2_1238:
	v_mul_f32_e32 v130, v141, v141
	v_mul_f32_e32 v131, v139, v139
	v_fmac_f32_e32 v130, v140, v140
	v_fmac_f32_e32 v131, v138, v138
	v_add_f32_e32 v130, v130, v131
	v_mul_f32_e32 v131, v171, v171
	v_mul_f32_e32 v132, v173, v173
	v_fmac_f32_e32 v131, v170, v170
	v_fmac_f32_e32 v132, v172, v172
	v_add_f32_e32 v131, v131, v132
	v_add_f32_e32 v130, v130, v131
	v_mul_f32_e32 v131, v175, v175
	v_mul_f32_e32 v132, v177, v177
	v_fmac_f32_e32 v131, v174, v174
	v_fmac_f32_e32 v132, v176, v176
	v_add_f32_e32 v131, v131, v132
	v_add_f32_e32 v136, v130, v131
	v_pk_mul_f32 v[130:131], v[180:181], v[180:181]
	v_pk_mul_f32 v[132:133], v[178:179], v[178:179]
	s_and_b64 s[0:1], exec, s[0:1]
	v_pk_mov_b32 v[134:135], v[132:133], v[130:131] op_sel:[1,0]
	v_mov_b32_e32 v133, v131
	v_pk_add_f32 v[130:131], v[134:135], v[132:133]
	s_ashr_i32 s11, s10, 31
	v_add_f32_e32 v130, v130, v131
	v_add_f32_e32 v130, v136, v130
	s_nop 1
	v_add_f32_dpp v130, v130, v130 quad_perm:[1,0,3,2] row_mask:0xf bank_mask:0xf
	s_nop 1
	v_add_f32_dpp v130, v130, v130 quad_perm:[2,3,0,1] row_mask:0xf bank_mask:0xf
	s_nop 1
	v_add_f32_dpp v130, v130, v130 row_half_mirror row_mask:0xf bank_mask:0xf
	s_nop 1
	v_add_f32_dpp v130, v130, v130 row_mirror row_mask:0xf bank_mask:0xf
	s_nop 1
	v_add_f32_dpp v130, v130, v130 row_bcast:15 row_mask:0xa bank_mask:0xf
	s_nop 1
	v_add_f32_dpp v130, v130, v130 row_bcast:31 row_mask:0xc bank_mask:0xf
	s_nop 0
	v_readlane_b32 s64, v130, 63
	s_nop 1
	v_mov_b32_e32 v132, s64
	s_waitcnt lgkmcnt(0)
	s_mov_b64 s[12:13], -1
	s_waitcnt vmcnt(7)
	v_pk_mul_f32 v[188:189], v[102:103], 0.5 op_sel_hi:[1,0]
	s_waitcnt vmcnt(6)
	v_pk_mul_f32 v[186:187], v[106:107], 0.5 op_sel_hi:[1,0]
	s_waitcnt vmcnt(4)
	v_pk_mul_f32 v[184:185], v[110:111], 0.5 op_sel_hi:[1,0]
	v_pk_mul_f32 v[130:131], v[96:97], 0.5 op_sel_hi:[1,0]
	v_fmamk_f32 v132, v132, 0x3a800000, v196
	v_mul_f32_e32 v133, 0x4b800000, v132
	v_cmp_gt_f32_e32 vcc, s25, v132
	s_nop 1
	v_cndmask_b32_e32 v132, v132, v133, vcc
	v_rsq_f32_e32 v134, v132
	v_pk_mul_f32 v[132:133], v[94:95], 0.5 op_sel_hi:[1,0]
	v_mul_f32_e32 v135, 0x45800000, v134
	v_cndmask_b32_e32 v182, v134, v135, vcc
	v_mov_b32_e32 v183, v182
	v_pk_mul_f32 v[134:135], v[138:139], v[182:183] op_sel_hi:[1,0]
	v_pk_mul_f32 v[136:137], v[140:141], v[182:183] op_sel_hi:[1,0]
	v_pk_mul_f32 v[134:135], v[4:5], v[134:135]
	v_pk_mul_f32 v[136:137], v[2:3], v[136:137]
	v_pk_fma_f32 v[116:117], v[130:131], v[134:135], v[116:117]
	v_pk_fma_f32 v[114:115], v[132:133], v[136:137], v[114:115]
	s_mov_b64 vcc, s[0:1]
	s_cbranch_vccz .Lrow2_1240
	v_mov_b32_e32 v138, v182
	v_mov_b32_e32 v139, v182
	v_pk_mul_f32 v[132:133], v[172:173], v[138:139]
	v_pk_mul_f32 v[134:135], v[170:171], v[182:183]
	v_pk_mul_f32 v[130:131], v[104:105], 0.5 op_sel_hi:[1,0]
	v_pk_mul_f32 v[132:133], v[8:9], v[132:133]
	v_pk_mul_f32 v[134:135], v[6:7], v[134:135]
	v_pk_mul_f32 v[136:137], v[176:177], v[138:139]
	v_pk_mul_f32 v[140:141], v[174:175], v[182:183]
	v_pk_fma_f32 v[132:133], v[130:131], v[132:133], v[120:121]
	v_pk_fma_f32 v[130:131], v[188:189], v[134:135], v[118:119]
	v_pk_mul_f32 v[134:135], v[108:109], 0.5 op_sel_hi:[1,0]
	v_pk_mul_f32 v[136:137], v[20:21], v[136:137]
	v_pk_mul_f32 v[140:141], v[18:19], v[140:141]
	v_pk_mul_f32 v[138:139], v[180:181], v[138:139]
	v_pk_mul_f32 v[200:201], v[178:179], v[182:183]
	s_lshl_b64 s[0:1], s[4:5], 12
	v_pk_fma_f32 v[136:137], v[134:135], v[136:137], v[124:125]
	v_pk_fma_f32 v[134:135], v[186:187], v[140:141], v[122:123]
	v_pk_mul_f32 v[140:141], v[112:113], 0.5 op_sel_hi:[1,0]
	v_pk_mul_f32 v[138:139], v[24:25], v[138:139]
	v_pk_mul_f32 v[200:201], v[22:23], v[200:201]
	v_lshl_add_u64 v[198:199], v[160:161], 0, s[0:1]
	v_pk_fma_f32 v[140:141], v[140:141], v[138:139], v[128:129]
	v_pk_fma_f32 v[138:139], v[184:185], v[200:201], v[126:127]
	global_store_dwordx4 v[198:199], v[114:117], off
	global_store_dwordx4 v[198:199], v[130:133], off offset:1024
	global_store_dwordx4 v[198:199], v[134:137], off offset:2048
	global_store_dwordx4 v[198:199], v[138:141], off offset:3072
	s_lshl_b64 s[2:3], s[10:11], 11
	s_mov_b64 s[12:13], 0

; #define GAS __attribute__((address_space(1)))
; DI unsigned pk2(float lo, float hi) { f32x2_t v = {lo, hi}; bf16x2_t b = __builtin_convertvector(v, bf16x2_t); return __builtin_bit_cast(unsigned, b); }
; DI float bflo(unsigned w) { return __uint_as_float(w << 16); }
; DI float bfhi(unsigned w) { return __uint_as_float(w & 0xffff0000u); }
; DI void phase_e(const Ctx& C, int nslab, int has_post, int pl, int ps, float pw, int has_pre, int ql, int qs, int nrows,
;                 const GAS float* xsrc, const GAS float* csrc, GAS float* xdst, GAS float* cdst, bool xs16, bool xd16) {
;     ...
;             f32x4 y[4]; float ss = 0.f;
; #pragma unroll
;             for (int j = 0; j < 4; ++j) {
;                 if (isx || nslab == 0) { y[j] = (f32x4){bflo(yw[j].x), bfhi(yw[j].x), bflo(yw[j].y), bfhi(yw[j].y)}; }
;                 else { y[j] = (f32x4){0.f, 0.f, 0.f, 0.f};
;                     for (int s = 0; s < nslab; ++s) { const u32x2 w = *(const GAS u32x2*)(YS + ((size_t)s * MC + (row - MX)) * 1024 + 256 * j + 4 * lane); y[j] += (f32x4){bflo(w.x), bfhi(w.x), bflo(w.y), bfhi(w.y)}; } }
;                 ss += (y[j][0] * y[j][0] + y[j][1] * y[j][1]) + (y[j][2] * y[j][2] + y[j][3] * y[j][3]); }
;             const float r = rsqrtf(wave_sum(ss) * (1.0f / 1024.0f) + EPS);
;             if (isx && xd16) { GAS bf16* d16 = (GAS bf16*)xdst + (size_t)row * 1024;
; #pragma unroll
;                 for (int j = 0; j < 4; ++j) { v[j] += pw * gt[j] * ((y[j] * r) * gpo[j]); u32x2 w; w.x = pk2(v[j][0], v[j][1]); w.y = pk2(v[j][2], v[j][3]); __builtin_nontemporal_store(w, (GAS u32x2*)(d16 + 256 * j + 4 * lane));
;                     v[j] = (f32x4){bflo(w.x), bfhi(w.x), bflo(w.y), bfhi(w.y)}; }
;             } else { GAS float* dst = isx ? xdst + (size_t)row * 1024 : cdst + (size_t)(row - MX) * 1024;
; #pragma unroll
;                 for (int j = 0; j < 4; ++j) { v[j] += pw * gt[j] * ((y[j] * r) * gpo[j]); __builtin_nontemporal_store(v[j], (GAS f32x4*)(dst + 256 * j + 4 * lane)); } }
.LBB0_1506:
	v_mul_f32_e32 v130, v141, v141
	v_mul_f32_e32 v131, v139, v139
	v_fmac_f32_e32 v130, v140, v140
	v_fmac_f32_e32 v131, v138, v138
	v_add_f32_e32 v130, v130, v131
	v_mul_f32_e32 v131, v171, v171
	v_mul_f32_e32 v132, v173, v173
	v_fmac_f32_e32 v131, v170, v170
	v_fmac_f32_e32 v132, v172, v172
	v_add_f32_e32 v131, v131, v132
	v_add_f32_e32 v130, v130, v131
	v_mul_f32_e32 v131, v175, v175
	v_mul_f32_e32 v132, v177, v177
	v_fmac_f32_e32 v131, v174, v174
	v_fmac_f32_e32 v132, v176, v176
	v_add_f32_e32 v131, v131, v132
	v_add_f32_e32 v136, v130, v131
	v_pk_mul_f32 v[130:131], v[180:181], v[180:181]
	v_pk_mul_f32 v[132:133], v[178:179], v[178:179]
	s_and_b64 s[0:1], exec, s[0:1]
	v_pk_mov_b32 v[134:135], v[132:133], v[130:131] op_sel:[1,0]
	v_mov_b32_e32 v133, v131
	v_pk_add_f32 v[130:131], v[134:135], v[132:133]
	s_ashr_i32 s11, s10, 31
	v_add_f32_e32 v130, v130, v131
	v_add_f32_e32 v130, v136, v130
	s_nop 1
	v_add_f32_dpp v130, v130, v130 quad_perm:[1,0,3,2] row_mask:0xf bank_mask:0xf
	s_nop 1
	v_add_f32_dpp v130, v130, v130 quad_perm:[2,3,0,1] row_mask:0xf bank_mask:0xf
	s_nop 1
	v_add_f32_dpp v130, v130, v130 row_half_mirror row_mask:0xf bank_mask:0xf
	s_nop 1
	v_add_f32_dpp v130, v130, v130 row_mirror row_mask:0xf bank_mask:0xf
	s_nop 1
	v_add_f32_dpp v130, v130, v130 row_bcast:15 row_mask:0xa bank_mask:0xf
	s_nop 1
	v_add_f32_dpp v130, v130, v130 row_bcast:31 row_mask:0xc bank_mask:0xf
	s_nop 0
	v_readlane_b32 s64, v130, 63
	s_nop 1
	v_mov_b32_e32 v132, s64
	s_waitcnt lgkmcnt(0)
	s_mov_b64 s[12:13], -1
	s_waitcnt vmcnt(7)
	v_pk_mul_f32 v[188:189], v[102:103], 0.5 op_sel_hi:[1,0]
	s_waitcnt vmcnt(6)
	v_pk_mul_f32 v[186:187], v[106:107], 0.5 op_sel_hi:[1,0]
	s_waitcnt vmcnt(4)
	v_pk_mul_f32 v[184:185], v[110:111], 0.5 op_sel_hi:[1,0]
	v_pk_mul_f32 v[130:131], v[96:97], 0.5 op_sel_hi:[1,0]
	v_fmamk_f32 v132, v132, 0x3a800000, v196
	v_mul_f32_e32 v133, 0x4b800000, v132
	v_cmp_gt_f32_e32 vcc, s27, v132
	s_nop 1
	v_cndmask_b32_e32 v132, v132, v133, vcc
	v_rsq_f32_e32 v134, v132
	v_pk_mul_f32 v[132:133], v[94:95], 0.5 op_sel_hi:[1,0]
	v_mul_f32_e32 v135, 0x45800000, v134
	v_cndmask_b32_e32 v182, v134, v135, vcc
	v_mov_b32_e32 v183, v182
	v_pk_mul_f32 v[134:135], v[138:139], v[182:183] op_sel_hi:[1,0]
	v_pk_mul_f32 v[136:137], v[140:141], v[182:183] op_sel_hi:[1,0]
	v_pk_mul_f32 v[134:135], v[4:5], v[134:135]
	v_pk_mul_f32 v[136:137], v[2:3], v[136:137]
	v_pk_fma_f32 v[100:101], v[130:131], v[134:135], v[100:101]
	v_pk_fma_f32 v[98:99], v[132:133], v[136:137], v[98:99]
	s_mov_b64 vcc, s[0:1]
	s_cbranch_vccz .LBB0_1508
	v_mov_b32_e32 v138, v182
	v_mov_b32_e32 v139, v182
	v_pk_mul_f32 v[132:133], v[172:173], v[138:139]
	v_pk_mul_f32 v[134:135], v[170:171], v[182:183]
	v_pk_mul_f32 v[130:131], v[104:105], 0.5 op_sel_hi:[1,0]
	v_pk_mul_f32 v[132:133], v[8:9], v[132:133]
	v_pk_mul_f32 v[134:135], v[6:7], v[134:135]
	v_pk_mul_f32 v[136:137], v[176:177], v[138:139]
	v_pk_mul_f32 v[140:141], v[174:175], v[182:183]
	v_pk_fma_f32 v[132:133], v[130:131], v[132:133], v[60:61]
	v_pk_fma_f32 v[130:131], v[188:189], v[134:135], v[58:59]
	v_pk_mul_f32 v[134:135], v[108:109], 0.5 op_sel_hi:[1,0]
	v_pk_mul_f32 v[136:137], v[20:21], v[136:137]
	v_pk_mul_f32 v[140:141], v[18:19], v[140:141]
	v_pk_mul_f32 v[138:139], v[180:181], v[138:139]
	v_pk_mul_f32 v[200:201], v[178:179], v[182:183]
	s_lshl_b64 s[0:1], s[4:5], 12
	v_pk_fma_f32 v[136:137], v[134:135], v[136:137], v[56:57]
	v_pk_fma_f32 v[134:135], v[186:187], v[140:141], v[54:55]
	v_pk_mul_f32 v[140:141], v[112:113], 0.5 op_sel_hi:[1,0]
	v_pk_mul_f32 v[138:139], v[24:25], v[138:139]
	v_pk_mul_f32 v[200:201], v[22:23], v[200:201]
	v_lshl_add_u64 v[198:199], v[160:161], 0, s[0:1]
	v_pk_fma_f32 v[140:141], v[140:141], v[138:139], v[48:49]
	v_pk_fma_f32 v[138:139], v[184:185], v[200:201], v[46:47]
	global_store_dwordx4 v[198:199], v[98:101], off
	global_store_dwordx4 v[198:199], v[130:133], off offset:1024
	global_store_dwordx4 v[198:199], v[134:137], off offset:2048
	global_store_dwordx4 v[198:199], v[138:141], off offset:3072
	s_lshl_b64 s[2:3], s[10:11], 11
	s_mov_b64 s[12:13], 0

; #define GAS __attribute__((address_space(1)))
; DI unsigned pk2(float lo, float hi) { f32x2_t v = {lo, hi}; bf16x2_t b = __builtin_convertvector(v, bf16x2_t); return __builtin_bit_cast(unsigned, b); }
; DI float bflo(unsigned w) { return __uint_as_float(w << 16); }
; DI float bfhi(unsigned w) { return __uint_as_float(w & 0xffff0000u); }
; DI void phase_e(const Ctx& C, int nslab, int has_post, int pl, int ps, float pw, int has_pre, int ql, int qs, int nrows,
;                 const GAS float* xsrc, const GAS float* csrc, GAS float* xdst, GAS float* cdst, bool xs16, bool xd16) {
;     ...
;             f32x4 y[4]; float ss = 0.f;
; #pragma unroll
;             for (int j = 0; j < 4; ++j) {
;                 if (isx || nslab == 0) { y[j] = (f32x4){bflo(yw[j].x), bfhi(yw[j].x), bflo(yw[j].y), bfhi(yw[j].y)}; }
;                 else { y[j] = (f32x4){0.f, 0.f, 0.f, 0.f};
;                     for (int s = 0; s < nslab; ++s) { const u32x2 w = *(const GAS u32x2*)(YS + ((size_t)s * MC + (row - MX)) * 1024 + 256 * j + 4 * lane); y[j] += (f32x4){bflo(w.x), bfhi(w.x), bflo(w.y), bfhi(w.y)}; } }
;                 ss += (y[j][0] * y[j][0] + y[j][1] * y[j][1]) + (y[j][2] * y[j][2] + y[j][3] * y[j][3]); }
;             const float r = rsqrtf(wave_sum(ss) * (1.0f / 1024.0f) + EPS);
;             if (isx && xd16) { GAS bf16* d16 = (GAS bf16*)xdst + (size_t)row * 1024;
; #pragma unroll
;                 for (int j = 0; j < 4; ++j) { v[j] += pw * gt[j] * ((y[j] * r) * gpo[j]); u32x2 w; w.x = pk2(v[j][0], v[j][1]); w.y = pk2(v[j][2], v[j][3]); __builtin_nontemporal_store(w, (GAS u32x2*)(d16 + 256 * j + 4 * lane));
;                     v[j] = (f32x4){bflo(w.x), bfhi(w.x), bflo(w.y), bfhi(w.y)}; }
;             } else { GAS float* dst = isx ? xdst + (size_t)row * 1024 : cdst + (size_t)(row - MX) * 1024;
; #pragma unroll
;                 for (int j = 0; j < 4; ++j) { v[j] += pw * gt[j] * ((y[j] * r) * gpo[j]); __builtin_nontemporal_store(v[j], (GAS f32x4*)(dst + 256 * j + 4 * lane)); } }
.Lrow1_1506:
	v_mul_f32_e32 v130, v141, v141
	v_mul_f32_e32 v131, v139, v139
	v_fmac_f32_e32 v130, v140, v140
	v_fmac_f32_e32 v131, v138, v138
	v_add_f32_e32 v130, v130, v131
	v_mul_f32_e32 v131, v171, v171
	v_mul_f32_e32 v132, v173, v173
	v_fmac_f32_e32 v131, v170, v170
	v_fmac_f32_e32 v132, v172, v172
	v_add_f32_e32 v131, v131, v132
	v_add_f32_e32 v130, v130, v131
	v_mul_f32_e32 v131, v175, v175
	v_mul_f32_e32 v132, v177, v177
	v_fmac_f32_e32 v131, v174, v174
	v_fmac_f32_e32 v132, v176, v176
	v_add_f32_e32 v131, v131, v132
	v_add_f32_e32 v136, v130, v131
	v_pk_mul_f32 v[130:131], v[180:181], v[180:181]
	v_pk_mul_f32 v[132:133], v[178:179], v[178:179]
	s_and_b64 s[0:1], exec, s[0:1]
	v_pk_mov_b32 v[134:135], v[132:133], v[130:131] op_sel:[1,0]
	v_mov_b32_e32 v133, v131
	v_pk_add_f32 v[130:131], v[134:135], v[132:133]
	s_ashr_i32 s11, s10, 31
	v_add_f32_e32 v130, v130, v131
	v_add_f32_e32 v130, v136, v130
	s_nop 1
	v_add_f32_dpp v130, v130, v130 quad_perm:[1,0,3,2] row_mask:0xf bank_mask:0xf
	s_nop 1
	v_add_f32_dpp v130, v130, v130 quad_perm:[2,3,0,1] row_mask:0xf bank_mask:0xf
	s_nop 1
	v_add_f32_dpp v130, v130, v130 row_half_mirror row_mask:0xf bank_mask:0xf
	s_nop 1
	v_add_f32_dpp v130, v130, v130 row_mirror row_mask:0xf bank_mask:0xf
	s_nop 1
	v_add_f32_dpp v130, v130, v130 row_bcast:15 row_mask:0xa bank_mask:0xf
	s_nop 1
	v_add_f32_dpp v130, v130, v130 row_bcast:31 row_mask:0xc bank_mask:0xf
	s_nop 0
	v_readlane_b32 s64, v130, 63
	s_nop 1
	v_mov_b32_e32 v132, s64
	s_waitcnt lgkmcnt(0)
	s_mov_b64 s[12:13], -1
	s_waitcnt vmcnt(7)
	v_pk_mul_f32 v[188:189], v[102:103], 0.5 op_sel_hi:[1,0]
	s_waitcnt vmcnt(6)
	v_pk_mul_f32 v[186:187], v[106:107], 0.5 op_sel_hi:[1,0]
	s_waitcnt vmcnt(4)
	v_pk_mul_f32 v[184:185], v[110:111], 0.5 op_sel_hi:[1,0]
	v_pk_mul_f32 v[130:131], v[96:97], 0.5 op_sel_hi:[1,0]
	v_fmamk_f32 v132, v132, 0x3a800000, v196
	v_mul_f32_e32 v133, 0x4b800000, v132
	v_cmp_gt_f32_e32 vcc, s27, v132
	s_nop 1
	v_cndmask_b32_e32 v132, v132, v133, vcc
	v_rsq_f32_e32 v134, v132
	v_pk_mul_f32 v[132:133], v[94:95], 0.5 op_sel_hi:[1,0]
	v_mul_f32_e32 v135, 0x45800000, v134
	v_cndmask_b32_e32 v182, v134, v135, vcc
	v_mov_b32_e32 v183, v182
	v_pk_mul_f32 v[134:135], v[138:139], v[182:183] op_sel_hi:[1,0]
	v_pk_mul_f32 v[136:137], v[140:141], v[182:183] op_sel_hi:[1,0]
	v_pk_mul_f32 v[134:135], v[4:5], v[134:135]
	v_pk_mul_f32 v[136:137], v[2:3], v[136:137]
	v_pk_fma_f32 v[36:37], v[130:131], v[134:135], v[36:37]
	v_pk_fma_f32 v[34:35], v[132:133], v[136:137], v[34:35]
	s_mov_b64 vcc, s[0:1]
	s_cbranch_vccz .Lrow1_1508
	v_mov_b32_e32 v138, v182
	v_mov_b32_e32 v139, v182
	v_pk_mul_f32 v[132:133], v[172:173], v[138:139]
	v_pk_mul_f32 v[134:135], v[170:171], v[182:183]
	v_pk_mul_f32 v[130:131], v[104:105], 0.5 op_sel_hi:[1,0]
	v_pk_mul_f32 v[132:133], v[8:9], v[132:133]
	v_pk_mul_f32 v[134:135], v[6:7], v[134:135]
	v_pk_mul_f32 v[136:137], v[176:177], v[138:139]
	v_pk_mul_f32 v[140:141], v[174:175], v[182:183]
	v_pk_fma_f32 v[132:133], v[130:131], v[132:133], v[40:41]
	v_pk_fma_f32 v[130:131], v[188:189], v[134:135], v[38:39]
	v_pk_mul_f32 v[134:135], v[108:109], 0.5 op_sel_hi:[1,0]
	v_pk_mul_f32 v[136:137], v[20:21], v[136:137]
	v_pk_mul_f32 v[140:141], v[18:19], v[140:141]
	v_pk_mul_f32 v[138:139], v[180:181], v[138:139]
	v_pk_mul_f32 v[200:201], v[178:179], v[182:183]
	s_lshl_b64 s[0:1], s[4:5], 12
	v_pk_fma_f32 v[136:137], v[134:135], v[136:137], v[44:45]
	v_pk_fma_f32 v[134:135], v[186:187], v[140:141], v[42:43]
	v_pk_mul_f32 v[140:141], v[112:113], 0.5 op_sel_hi:[1,0]
	v_pk_mul_f32 v[138:139], v[24:25], v[138:139]
	v_pk_mul_f32 v[200:201], v[22:23], v[200:201]
	v_lshl_add_u64 v[198:199], v[160:161], 0, s[0:1]
	v_pk_fma_f32 v[140:141], v[140:141], v[138:139], v[52:53]
	v_pk_fma_f32 v[138:139], v[184:185], v[200:201], v[50:51]
	global_store_dwordx4 v[198:199], v[34:37], off
	global_store_dwordx4 v[198:199], v[130:133], off offset:1024
	global_store_dwordx4 v[198:199], v[134:137], off offset:2048
	global_store_dwordx4 v[198:199], v[138:141], off offset:3072
	s_lshl_b64 s[2:3], s[10:11], 11
	s_mov_b64 s[12:13], 0

; #define GAS __attribute__((address_space(1)))
; DI unsigned pk2(float lo, float hi) { f32x2_t v = {lo, hi}; bf16x2_t b = __builtin_convertvector(v, bf16x2_t); return __builtin_bit_cast(unsigned, b); }
; DI float bflo(unsigned w) { return __uint_as_float(w << 16); }
; DI float bfhi(unsigned w) { return __uint_as_float(w & 0xffff0000u); }
; DI void phase_e(const Ctx& C, int nslab, int has_post, int pl, int ps, float pw, int has_pre, int ql, int qs, int nrows,
;                 const GAS float* xsrc, const GAS float* csrc, GAS float* xdst, GAS float* cdst, bool xs16, bool xd16) {
;     ...
;             f32x4 y[4]; float ss = 0.f;
; #pragma unroll
;             for (int j = 0; j < 4; ++j) {
;                 if (isx || nslab == 0) { y[j] = (f32x4){bflo(yw[j].x), bfhi(yw[j].x), bflo(yw[j].y), bfhi(yw[j].y)}; }
;                 else { y[j] = (f32x4){0.f, 0.f, 0.f, 0.f};
;                     for (int s = 0; s < nslab; ++s) { const u32x2 w = *(const GAS u32x2*)(YS + ((size_t)s * MC + (row - MX)) * 1024 + 256 * j + 4 * lane); y[j] += (f32x4){bflo(w.x), bfhi(w.x), bflo(w.y), bfhi(w.y)}; } }
;                 ss += (y[j][0] * y[j][0] + y[j][1] * y[j][1]) + (y[j][2] * y[j][2] + y[j][3] * y[j][3]); }
;             const float r = rsqrtf(wave_sum(ss) * (1.0f / 1024.0f) + EPS);
;             if (isx && xd16) { GAS bf16* d16 = (GAS bf16*)xdst + (size_t)row * 1024;
; #pragma unroll
;                 for (int j = 0; j < 4; ++j) { v[j] += pw * gt[j] * ((y[j] * r) * gpo[j]); u32x2 w; w.x = pk2(v[j][0], v[j][1]); w.y = pk2(v[j][2], v[j][3]); __builtin_nontemporal_store(w, (GAS u32x2*)(d16 + 256 * j + 4 * lane));
;                     v[j] = (f32x4){bflo(w.x), bfhi(w.x), bflo(w.y), bfhi(w.y)}; }
;             } else { GAS float* dst = isx ? xdst + (size_t)row * 1024 : cdst + (size_t)(row - MX) * 1024;
; #pragma unroll
;                 for (int j = 0; j < 4; ++j) { v[j] += pw * gt[j] * ((y[j] * r) * gpo[j]); __builtin_nontemporal_store(v[j], (GAS f32x4*)(dst + 256 * j + 4 * lane)); } }
.Lrow2_1506:
	v_mul_f32_e32 v130, v141, v141
	v_mul_f32_e32 v131, v139, v139
	v_fmac_f32_e32 v130, v140, v140
	v_fmac_f32_e32 v131, v138, v138
	v_add_f32_e32 v130, v130, v131
	v_mul_f32_e32 v131, v171, v171
	v_mul_f32_e32 v132, v173, v173
	v_fmac_f32_e32 v131, v170, v170
	v_fmac_f32_e32 v132, v172, v172
	v_add_f32_e32 v131, v131, v132
	v_add_f32_e32 v130, v130, v131
	v_mul_f32_e32 v131, v175, v175
	v_mul_f32_e32 v132, v177, v177
	v_fmac_f32_e32 v131, v174, v174
	v_fmac_f32_e32 v132, v176, v176
	v_add_f32_e32 v131, v131, v132
	v_add_f32_e32 v136, v130, v131
	v_pk_mul_f32 v[130:131], v[180:181], v[180:181]
	v_pk_mul_f32 v[132:133], v[178:179], v[178:179]
	s_and_b64 s[0:1], exec, s[0:1]
	v_pk_mov_b32 v[134:135], v[132:133], v[130:131] op_sel:[1,0]
	v_mov_b32_e32 v133, v131
	v_pk_add_f32 v[130:131], v[134:135], v[132:133]
	s_ashr_i32 s11, s10, 31
	v_add_f32_e32 v130, v130, v131
	v_add_f32_e32 v130, v136, v130
	s_nop 1
	v_add_f32_dpp v130, v130, v130 quad_perm:[1,0,3,2] row_mask:0xf bank_mask:0xf
	s_nop 1
	v_add_f32_dpp v130, v130, v130 quad_perm:[2,3,0,1] row_mask:0xf bank_mask:0xf
	s_nop 1
	v_add_f32_dpp v130, v130, v130 row_half_mirror row_mask:0xf bank_mask:0xf
	s_nop 1
	v_add_f32_dpp v130, v130, v130 row_mirror row_mask:0xf bank_mask:0xf
	s_nop 1
	v_add_f32_dpp v130, v130, v130 row_bcast:15 row_mask:0xa bank_mask:0xf
	s_nop 1
	v_add_f32_dpp v130, v130, v130 row_bcast:31 row_mask:0xc bank_mask:0xf
	s_nop 0
	v_readlane_b32 s64, v130, 63
	s_nop 1
	v_mov_b32_e32 v132, s64
	s_waitcnt lgkmcnt(0)
	s_mov_b64 s[12:13], -1
	s_waitcnt vmcnt(7)
	v_pk_mul_f32 v[188:189], v[102:103], 0.5 op_sel_hi:[1,0]
	s_waitcnt vmcnt(6)
	v_pk_mul_f32 v[186:187], v[106:107], 0.5 op_sel_hi:[1,0]
	s_waitcnt vmcnt(4)
	v_pk_mul_f32 v[184:185], v[110:111], 0.5 op_sel_hi:[1,0]
	v_pk_mul_f32 v[130:131], v[96:97], 0.5 op_sel_hi:[1,0]
	v_fmamk_f32 v132, v132, 0x3a800000, v196
	v_mul_f32_e32 v133, 0x4b800000, v132
	v_cmp_gt_f32_e32 vcc, s27, v132
	s_nop 1
	v_cndmask_b32_e32 v132, v132, v133, vcc
	v_rsq_f32_e32 v134, v132
	v_pk_mul_f32 v[132:133], v[94:95], 0.5 op_sel_hi:[1,0]
	v_mul_f32_e32 v135, 0x45800000, v134
	v_cndmask_b32_e32 v182, v134, v135, vcc
	v_mov_b32_e32 v183, v182
	v_pk_mul_f32 v[134:135], v[138:139], v[182:183] op_sel_hi:[1,0]
	v_pk_mul_f32 v[136:137], v[140:141], v[182:183] op_sel_hi:[1,0]
	v_pk_mul_f32 v[134:135], v[4:5], v[134:135]
	v_pk_mul_f32 v[136:137], v[2:3], v[136:137]
	v_pk_fma_f32 v[116:117], v[130:131], v[134:135], v[116:117]
	v_pk_fma_f32 v[114:115], v[132:133], v[136:137], v[114:115]
	s_mov_b64 vcc, s[0:1]
	s_cbranch_vccz .Lrow2_1508
	v_mov_b32_e32 v138, v182
	v_mov_b32_e32 v139, v182
	v_pk_mul_f32 v[132:133], v[172:173], v[138:139]
	v_pk_mul_f32 v[134:135], v[170:171], v[182:183]
	v_pk_mul_f32 v[130:131], v[104:105], 0.5 op_sel_hi:[1,0]
	v_pk_mul_f32 v[132:133], v[8:9], v[132:133]
	v_pk_mul_f32 v[134:135], v[6:7], v[134:135]
	v_pk_mul_f32 v[136:137], v[176:177], v[138:139]
	v_pk_mul_f32 v[140:141], v[174:175], v[182:183]
	v_pk_fma_f32 v[132:133], v[130:131], v[132:133], v[120:121]
	v_pk_fma_f32 v[130:131], v[188:189], v[134:135], v[118:119]
	v_pk_mul_f32 v[134:135], v[108:109], 0.5 op_sel_hi:[1,0]
	v_pk_mul_f32 v[136:137], v[20:21], v[136:137]
	v_pk_mul_f32 v[140:141], v[18:19], v[140:141]
	v_pk_mul_f32 v[138:139], v[180:181], v[138:139]
	v_pk_mul_f32 v[200:201], v[178:179], v[182:183]
	s_lshl_b64 s[0:1], s[4:5], 12
	v_pk_fma_f32 v[136:137], v[134:135], v[136:137], v[124:125]
	v_pk_fma_f32 v[134:135], v[186:187], v[140:141], v[122:123]
	v_pk_mul_f32 v[140:141], v[112:113], 0.5 op_sel_hi:[1,0]
	v_pk_mul_f32 v[138:139], v[24:25], v[138:139]
	v_pk_mul_f32 v[200:201], v[22:23], v[200:201]
	v_lshl_add_u64 v[198:199], v[160:161], 0, s[0:1]
	v_pk_fma_f32 v[140:141], v[140:141], v[138:139], v[128:129]
	v_pk_fma_f32 v[138:139], v[184:185], v[200:201], v[126:127]
	global_store_dwordx4 v[198:199], v[114:117], off
	global_store_dwordx4 v[198:199], v[130:133], off offset:1024
	global_store_dwordx4 v[198:199], v[134:137], off offset:2048
	global_store_dwordx4 v[198:199], v[138:141], off offset:3072
	s_lshl_b64 s[2:3], s[10:11], 11
	s_mov_b64 s[12:13], 0

; #define GAS __attribute__((address_space(1)))
; DI unsigned pk2(float lo, float hi) { f32x2_t v = {lo, hi}; bf16x2_t b = __builtin_convertvector(v, bf16x2_t); return __builtin_bit_cast(unsigned, b); }
; DI float bflo(unsigned w) { return __uint_as_float(w << 16); }
; DI float bfhi(unsigned w) { return __uint_as_float(w & 0xffff0000u); }
; DI void phase_e(const Ctx& C, int nslab, int has_post, int pl, int ps, float pw, int has_pre, int ql, int qs, int nrows,
;                 const GAS float* xsrc, const GAS float* csrc, GAS float* xdst, GAS float* cdst, bool xs16, bool xd16) {
;     ...
;             f32x4 y[4]; float ss = 0.f;
; #pragma unroll
;             for (int j = 0; j < 4; ++j) {
;                 if (isx || nslab == 0) { y[j] = (f32x4){bflo(yw[j].x), bfhi(yw[j].x), bflo(yw[j].y), bfhi(yw[j].y)}; }
;                 else { y[j] = (f32x4){0.f, 0.f, 0.f, 0.f};
;                     for (int s = 0; s < nslab; ++s) { const u32x2 w = *(const GAS u32x2*)(YS + ((size_t)s * MC + (row - MX)) * 1024 + 256 * j + 4 * lane); y[j] += (f32x4){bflo(w.x), bfhi(w.x), bflo(w.y), bfhi(w.y)}; } }
;                 ss += (y[j][0] * y[j][0] + y[j][1] * y[j][1]) + (y[j][2] * y[j][2] + y[j][3] * y[j][3]); }
;             const float r = rsqrtf(wave_sum(ss) * (1.0f / 1024.0f) + EPS);
;             if (isx && xd16) { GAS bf16* d16 = (GAS bf16*)xdst + (size_t)row * 1024;
; #pragma unroll
;                 for (int j = 0; j < 4; ++j) { v[j] += pw * gt[j] * ((y[j] * r) * gpo[j]); u32x2 w; w.x = pk2(v[j][0], v[j][1]); w.y = pk2(v[j][2], v[j][3]); __builtin_nontemporal_store(w, (GAS u32x2*)(d16 + 256 * j + 4 * lane));
;                     v[j] = (f32x4){bflo(w.x), bfhi(w.x), bflo(w.y), bfhi(w.y)}; }
;             } else { GAS float* dst = isx ? xdst + (size_t)row * 1024 : cdst + (size_t)(row - MX) * 1024;
; #pragma unroll
;                 for (int j = 0; j < 4; ++j) { v[j] += pw * gt[j] * ((y[j] * r) * gpo[j]); __builtin_nontemporal_store(v[j], (GAS f32x4*)(dst + 256 * j + 4 * lane)); } }
.LBB0_2218:
	v_and_b32_e32 v189, 0xffff0000, v137
	v_and_b32_e32 v188, 0xffff0000, v136
	v_and_b32_e32 v185, 0xffff0000, v135
	v_and_b32_e32 v184, 0xffff0000, v134
	v_lshlrev_b32_e32 v187, 16, v137
	v_lshlrev_b32_e32 v186, 16, v136
	v_pk_mul_f32 v[136:137], v[188:189], v[188:189]
	v_lshlrev_b32_e32 v183, 16, v135
	v_lshlrev_b32_e32 v182, 16, v134
	v_pk_mul_f32 v[134:135], v[184:185], v[184:185]
	v_lshlrev_b32_e32 v178, 16, v132
	v_and_b32_e32 v179, 0xffff0000, v132
	v_lshlrev_b32_e32 v180, 16, v133
	v_lshlrev_b32_e32 v174, 16, v130
	v_pk_fma_f32 v[136:137], v[186:187], v[186:187], v[136:137]
	v_pk_fma_f32 v[134:135], v[182:183], v[182:183], v[134:135]
	v_mul_f32_e32 v139, v178, v178
	v_mul_f32_e32 v141, v179, v179
	v_and_b32_e32 v181, 0xffff0000, v133
	v_mul_f32_e32 v132, v180, v180
	v_mov_b32_e32 v138, v174
	v_mov_b32_e32 v140, v174
	v_pk_add_f32 v[136:137], v[136:137], v[136:137] op_sel_hi:[0,1]
	v_pk_add_f32 v[134:135], v[134:135], v[134:135] op_sel_hi:[0,1]
	v_pk_fma_f32 v[132:133], v[180:181], v[180:181], v[132:133] op_sel_hi:[1,1,0]
	v_and_b32_e32 v175, 0xffff0000, v130
	v_lshlrev_b32_e32 v176, 16, v131
	v_and_b32_e32 v177, 0xffff0000, v131
	v_pk_add_f32 v[138:139], v[138:139], v[140:141]
	v_mul_f32_e32 v132, v175, v175
	v_mul_f32_e32 v134, v176, v176
	v_mul_f32_e32 v136, v177, v177
	v_mul_f32_e32 v130, v174, v174
	v_mov_b32_e32 v131, v139
	v_pk_add_f32 v[130:131], v[130:131], v[132:133]
	v_pk_add_f32 v[132:133], v[134:135], v[136:137]
	s_ashr_i32 s7, s6, 31
	v_pk_add_f32 v[130:131], v[130:131], v[132:133]
	s_cmpk_gt_i32 s6, 0x7fff
	v_add_f32_e32 v130, v130, v131
	s_nop 1
	v_add_f32_dpp v130, v130, v130 quad_perm:[1,0,3,2] row_mask:0xf bank_mask:0xf
	s_nop 1
	v_add_f32_dpp v130, v130, v130 quad_perm:[2,3,0,1] row_mask:0xf bank_mask:0xf
	s_nop 1
	v_add_f32_dpp v130, v130, v130 row_half_mirror row_mask:0xf bank_mask:0xf
	s_nop 1
	v_add_f32_dpp v130, v130, v130 row_mirror row_mask:0xf bank_mask:0xf
	s_nop 1
	v_add_f32_dpp v130, v130, v130 row_bcast:15 row_mask:0xa bank_mask:0xf
	s_nop 1
	v_add_f32_dpp v130, v130, v130 row_bcast:31 row_mask:0xc bank_mask:0xf
	s_nop 0
	v_readlane_b32 s64, v130, 63
	s_nop 1
	v_mov_b32_e32 v130, s64
	s_waitcnt lgkmcnt(0)
	s_mov_b64 s[10:11], -1
	v_fmamk_f32 v130, v130, 0x3a800000, v197
	v_mul_f32_e32 v131, 0x4b800000, v130
	v_cmp_gt_f32_e32 vcc, s22, v130
	s_nop 1
	v_cndmask_b32_e32 v130, v130, v131, vcc
	v_rsq_f32_e32 v130, v130
	s_nop 0
	v_mul_f32_e32 v131, 0x45800000, v130
	v_cndmask_b32_e32 v190, v130, v131, vcc
	s_cbranch_scc0 .LBB0_2220
	v_mov_b32_e32 v130, v187
	v_mov_b32_e32 v131, v189
	v_mov_b32_e32 v132, v186
	v_mov_b32_e32 v133, v188
	v_pk_mul_f32 v[130:131], v[130:131], v[190:191] op_sel_hi:[1,0]
	v_pk_mul_f32 v[132:133], v[132:133], v[190:191] op_sel_hi:[1,0]
	v_pk_mul_f32 v[130:131], v[4:5], v[130:131]
	v_pk_mul_f32 v[134:135], v[2:3], v[132:133]
	s_waitcnt vmcnt(11)
	v_pk_fma_f32 v[132:133], v[100:101], v[130:131], v[64:65]
	v_pk_fma_f32 v[130:131], v[98:99], v[134:135], v[62:63]
	v_mov_b32_e32 v134, v183
	v_mov_b32_e32 v135, v185
	v_mov_b32_e32 v136, v182
	v_mov_b32_e32 v137, v184
	v_pk_mul_f32 v[134:135], v[134:135], v[190:191] op_sel_hi:[1,0]
	v_pk_mul_f32 v[136:137], v[136:137], v[190:191] op_sel_hi:[1,0]
	v_pk_mul_f32 v[134:135], v[8:9], v[134:135]
	v_pk_mul_f32 v[138:139], v[6:7], v[136:137]
	s_add_i32 s0, s6, 0xffff8000
	s_waitcnt vmcnt(7)
	v_pk_fma_f32 v[136:137], v[104:105], v[134:135], v[60:61]
	v_pk_fma_f32 v[134:135], v[102:103], v[138:139], v[58:59]
	v_pk_mul_f32 v[138:139], v[178:179], v[190:191] op_sel_hi:[1,0]
	v_pk_mul_f32 v[140:141], v[180:181], v[190:191] op_sel_hi:[1,0]
	v_pk_mul_f32 v[142:143], v[176:177], v[190:191] op_sel_hi:[1,0]
	v_pk_mul_f32 v[144:145], v[174:175], v[190:191] op_sel_hi:[1,0]
	s_lshl_b64 s[8:9], s[0:1], 12
	v_pk_mul_f32 v[138:139], v[18:19], v[138:139]
	v_pk_mul_f32 v[140:141], v[20:21], v[140:141]
	v_pk_mul_f32 v[200:201], v[22:23], v[144:145]
	v_pk_mul_f32 v[142:143], v[24:25], v[142:143]
	v_lshl_add_u64 v[198:199], v[164:165], 0, s[8:9]
	s_waitcnt vmcnt(6)
	v_pk_fma_f32 v[140:141], v[108:109], v[140:141], v[56:57]
	v_pk_fma_f32 v[138:139], v[106:107], v[138:139], v[54:55]
	s_waitcnt vmcnt(4)
	v_pk_fma_f32 v[144:145], v[112:113], v[142:143], v[52:53]
	v_pk_fma_f32 v[142:143], v[110:111], v[200:201], v[50:51]
	global_store_dwordx4 v[198:199], v[130:133], off
	global_store_dwordx4 v[198:199], v[134:137], off offset:1024
	global_store_dwordx4 v[198:199], v[138:141], off offset:2048
	global_store_dwordx4 v[198:199], v[142:145], off offset:3072
	s_lshl_b64 s[8:9], s[6:7], 11
	s_mov_b64 s[10:11], 0

; #define GAS __attribute__((address_space(1)))
; DI unsigned pk2(float lo, float hi) { f32x2_t v = {lo, hi}; bf16x2_t b = __builtin_convertvector(v, bf16x2_t); return __builtin_bit_cast(unsigned, b); }
; DI float bflo(unsigned w) { return __uint_as_float(w << 16); }
; DI float bfhi(unsigned w) { return __uint_as_float(w & 0xffff0000u); }
; DI void phase_e(const Ctx& C, int nslab, int has_post, int pl, int ps, float pw, int has_pre, int ql, int qs, int nrows,
;                 const GAS float* xsrc, const GAS float* csrc, GAS float* xdst, GAS float* cdst, bool xs16, bool xd16) {
;     ...
;             f32x4 y[4]; float ss = 0.f;
; #pragma unroll
;             for (int j = 0; j < 4; ++j) {
;                 if (isx || nslab == 0) { y[j] = (f32x4){bflo(yw[j].x), bfhi(yw[j].x), bflo(yw[j].y), bfhi(yw[j].y)}; }
;                 else { y[j] = (f32x4){0.f, 0.f, 0.f, 0.f};
;                     for (int s = 0; s < nslab; ++s) { const u32x2 w = *(const GAS u32x2*)(YS + ((size_t)s * MC + (row - MX)) * 1024 + 256 * j + 4 * lane); y[j] += (f32x4){bflo(w.x), bfhi(w.x), bflo(w.y), bfhi(w.y)}; } }
;                 ss += (y[j][0] * y[j][0] + y[j][1] * y[j][1]) + (y[j][2] * y[j][2] + y[j][3] * y[j][3]); }
;             const float r = rsqrtf(wave_sum(ss) * (1.0f / 1024.0f) + EPS);
;             if (isx && xd16) { GAS bf16* d16 = (GAS bf16*)xdst + (size_t)row * 1024;
; #pragma unroll
;                 for (int j = 0; j < 4; ++j) { v[j] += pw * gt[j] * ((y[j] * r) * gpo[j]); u32x2 w; w.x = pk2(v[j][0], v[j][1]); w.y = pk2(v[j][2], v[j][3]); __builtin_nontemporal_store(w, (GAS u32x2*)(d16 + 256 * j + 4 * lane));
;                     v[j] = (f32x4){bflo(w.x), bfhi(w.x), bflo(w.y), bfhi(w.y)}; }
;             } else { GAS float* dst = isx ? xdst + (size_t)row * 1024 : cdst + (size_t)(row - MX) * 1024;
; #pragma unroll
;                 for (int j = 0; j < 4; ++j) { v[j] += pw * gt[j] * ((y[j] * r) * gpo[j]); __builtin_nontemporal_store(v[j], (GAS f32x4*)(dst + 256 * j + 4 * lane)); } }
.Lrow1_2218:
	v_and_b32_e32 v189, 0xffff0000, v137
	v_and_b32_e32 v188, 0xffff0000, v136
	v_and_b32_e32 v185, 0xffff0000, v135
	v_and_b32_e32 v184, 0xffff0000, v134
	v_lshlrev_b32_e32 v187, 16, v137
	v_lshlrev_b32_e32 v186, 16, v136
	v_pk_mul_f32 v[136:137], v[188:189], v[188:189]
	v_lshlrev_b32_e32 v183, 16, v135
	v_lshlrev_b32_e32 v182, 16, v134
	v_pk_mul_f32 v[134:135], v[184:185], v[184:185]
	v_lshlrev_b32_e32 v178, 16, v132
	v_and_b32_e32 v179, 0xffff0000, v132
	v_lshlrev_b32_e32 v180, 16, v133
	v_lshlrev_b32_e32 v174, 16, v130
	v_pk_fma_f32 v[136:137], v[186:187], v[186:187], v[136:137]
	v_pk_fma_f32 v[134:135], v[182:183], v[182:183], v[134:135]
	v_mul_f32_e32 v139, v178, v178
	v_mul_f32_e32 v141, v179, v179
	v_and_b32_e32 v181, 0xffff0000, v133
	v_mul_f32_e32 v132, v180, v180
	v_mov_b32_e32 v138, v174
	v_mov_b32_e32 v140, v174
	v_pk_add_f32 v[136:137], v[136:137], v[136:137] op_sel_hi:[0,1]
	v_pk_add_f32 v[134:135], v[134:135], v[134:135] op_sel_hi:[0,1]
	v_pk_fma_f32 v[132:133], v[180:181], v[180:181], v[132:133] op_sel_hi:[1,1,0]
	v_and_b32_e32 v175, 0xffff0000, v130
	v_lshlrev_b32_e32 v176, 16, v131
	v_and_b32_e32 v177, 0xffff0000, v131
	v_pk_add_f32 v[138:139], v[138:139], v[140:141]
	v_mul_f32_e32 v132, v175, v175
	v_mul_f32_e32 v134, v176, v176
	v_mul_f32_e32 v136, v177, v177
	v_mul_f32_e32 v130, v174, v174
	v_mov_b32_e32 v131, v139
	v_pk_add_f32 v[130:131], v[130:131], v[132:133]
	v_pk_add_f32 v[132:133], v[134:135], v[136:137]
	s_ashr_i32 s7, s6, 31
	v_pk_add_f32 v[130:131], v[130:131], v[132:133]
	s_cmpk_gt_i32 s6, 0x7fff
	v_add_f32_e32 v130, v130, v131
	s_nop 1
	v_add_f32_dpp v130, v130, v130 quad_perm:[1,0,3,2] row_mask:0xf bank_mask:0xf
	s_nop 1
	v_add_f32_dpp v130, v130, v130 quad_perm:[2,3,0,1] row_mask:0xf bank_mask:0xf
	s_nop 1
	v_add_f32_dpp v130, v130, v130 row_half_mirror row_mask:0xf bank_mask:0xf
	s_nop 1
	v_add_f32_dpp v130, v130, v130 row_mirror row_mask:0xf bank_mask:0xf
	s_nop 1
	v_add_f32_dpp v130, v130, v130 row_bcast:15 row_mask:0xa bank_mask:0xf
	s_nop 1
	v_add_f32_dpp v130, v130, v130 row_bcast:31 row_mask:0xc bank_mask:0xf
	s_nop 0
	v_readlane_b32 s64, v130, 63
	s_nop 1
	v_mov_b32_e32 v130, s64
	s_waitcnt lgkmcnt(0)
	s_mov_b64 s[10:11], -1
	v_fmamk_f32 v130, v130, 0x3a800000, v197
	v_mul_f32_e32 v131, 0x4b800000, v130
	v_cmp_gt_f32_e32 vcc, s22, v130
	s_nop 1
	v_cndmask_b32_e32 v130, v130, v131, vcc
	v_rsq_f32_e32 v130, v130
	s_nop 0
	v_mul_f32_e32 v131, 0x45800000, v130
	v_cndmask_b32_e32 v190, v130, v131, vcc
	s_cbranch_scc0 .Lrow1_2220
	v_mov_b32_e32 v130, v187
	v_mov_b32_e32 v131, v189
	v_mov_b32_e32 v132, v186
	v_mov_b32_e32 v133, v188
	v_pk_mul_f32 v[130:131], v[130:131], v[190:191] op_sel_hi:[1,0]
	v_pk_mul_f32 v[132:133], v[132:133], v[190:191] op_sel_hi:[1,0]
	v_pk_mul_f32 v[130:131], v[4:5], v[130:131]
	v_pk_mul_f32 v[134:135], v[2:3], v[132:133]
	s_waitcnt vmcnt(11)
	v_pk_fma_f32 v[132:133], v[100:101], v[130:131], v[36:37]
	v_pk_fma_f32 v[130:131], v[98:99], v[134:135], v[34:35]
	v_mov_b32_e32 v134, v183
	v_mov_b32_e32 v135, v185
	v_mov_b32_e32 v136, v182
	v_mov_b32_e32 v137, v184
	v_pk_mul_f32 v[134:135], v[134:135], v[190:191] op_sel_hi:[1,0]
	v_pk_mul_f32 v[136:137], v[136:137], v[190:191] op_sel_hi:[1,0]
	v_pk_mul_f32 v[134:135], v[8:9], v[134:135]
	v_pk_mul_f32 v[138:139], v[6:7], v[136:137]
	s_add_i32 s0, s6, 0xffff8000
	s_waitcnt vmcnt(7)
	v_pk_fma_f32 v[136:137], v[104:105], v[134:135], v[40:41]
	v_pk_fma_f32 v[134:135], v[102:103], v[138:139], v[38:39]
	v_pk_mul_f32 v[138:139], v[178:179], v[190:191] op_sel_hi:[1,0]
	v_pk_mul_f32 v[140:141], v[180:181], v[190:191] op_sel_hi:[1,0]
	v_pk_mul_f32 v[142:143], v[176:177], v[190:191] op_sel_hi:[1,0]
	v_pk_mul_f32 v[144:145], v[174:175], v[190:191] op_sel_hi:[1,0]
	s_lshl_b64 s[8:9], s[0:1], 12
	v_pk_mul_f32 v[138:139], v[18:19], v[138:139]
	v_pk_mul_f32 v[140:141], v[20:21], v[140:141]
	v_pk_mul_f32 v[200:201], v[22:23], v[144:145]
	v_pk_mul_f32 v[142:143], v[24:25], v[142:143]
	v_lshl_add_u64 v[198:199], v[164:165], 0, s[8:9]
	s_waitcnt vmcnt(6)
	v_pk_fma_f32 v[140:141], v[108:109], v[140:141], v[44:45]
	v_pk_fma_f32 v[138:139], v[106:107], v[138:139], v[42:43]
	s_waitcnt vmcnt(4)
	v_pk_fma_f32 v[144:145], v[112:113], v[142:143], v[48:49]
	v_pk_fma_f32 v[142:143], v[110:111], v[200:201], v[46:47]
	global_store_dwordx4 v[198:199], v[130:133], off
	global_store_dwordx4 v[198:199], v[134:137], off offset:1024
	global_store_dwordx4 v[198:199], v[138:141], off offset:2048
	global_store_dwordx4 v[198:199], v[142:145], off offset:3072
	s_lshl_b64 s[8:9], s[6:7], 11
	s_mov_b64 s[10:11], 0

; #define GAS __attribute__((address_space(1)))
; DI unsigned pk2(float lo, float hi) { f32x2_t v = {lo, hi}; bf16x2_t b = __builtin_convertvector(v, bf16x2_t); return __builtin_bit_cast(unsigned, b); }
; DI float bflo(unsigned w) { return __uint_as_float(w << 16); }
; DI float bfhi(unsigned w) { return __uint_as_float(w & 0xffff0000u); }
; DI void phase_e(const Ctx& C, int nslab, int has_post, int pl, int ps, float pw, int has_pre, int ql, int qs, int nrows,
;                 const GAS float* xsrc, const GAS float* csrc, GAS float* xdst, GAS float* cdst, bool xs16, bool xd16) {
;     ...
;             f32x4 y[4]; float ss = 0.f;
; #pragma unroll
;             for (int j = 0; j < 4; ++j) {
;                 if (isx || nslab == 0) { y[j] = (f32x4){bflo(yw[j].x), bfhi(yw[j].x), bflo(yw[j].y), bfhi(yw[j].y)}; }
;                 else { y[j] = (f32x4){0.f, 0.f, 0.f, 0.f};
;                     for (int s = 0; s < nslab; ++s) { const u32x2 w = *(const GAS u32x2*)(YS + ((size_t)s * MC + (row - MX)) * 1024 + 256 * j + 4 * lane); y[j] += (f32x4){bflo(w.x), bfhi(w.x), bflo(w.y), bfhi(w.y)}; } }
;                 ss += (y[j][0] * y[j][0] + y[j][1] * y[j][1]) + (y[j][2] * y[j][2] + y[j][3] * y[j][3]); }
;             const float r = rsqrtf(wave_sum(ss) * (1.0f / 1024.0f) + EPS);
;             if (isx && xd16) { GAS bf16* d16 = (GAS bf16*)xdst + (size_t)row * 1024;
; #pragma unroll
;                 for (int j = 0; j < 4; ++j) { v[j] += pw * gt[j] * ((y[j] * r) * gpo[j]); u32x2 w; w.x = pk2(v[j][0], v[j][1]); w.y = pk2(v[j][2], v[j][3]); __builtin_nontemporal_store(w, (GAS u32x2*)(d16 + 256 * j + 4 * lane));
;                     v[j] = (f32x4){bflo(w.x), bfhi(w.x), bflo(w.y), bfhi(w.y)}; }
;             } else { GAS float* dst = isx ? xdst + (size_t)row * 1024 : cdst + (size_t)(row - MX) * 1024;
; #pragma unroll
;                 for (int j = 0; j < 4; ++j) { v[j] += pw * gt[j] * ((y[j] * r) * gpo[j]); __builtin_nontemporal_store(v[j], (GAS f32x4*)(dst + 256 * j + 4 * lane)); } }
.Lrow2_2218:
	v_and_b32_e32 v189, 0xffff0000, v137
	v_and_b32_e32 v188, 0xffff0000, v136
	v_and_b32_e32 v185, 0xffff0000, v135
	v_and_b32_e32 v184, 0xffff0000, v134
	v_lshlrev_b32_e32 v187, 16, v137
	v_lshlrev_b32_e32 v186, 16, v136
	v_pk_mul_f32 v[136:137], v[188:189], v[188:189]
	v_lshlrev_b32_e32 v183, 16, v135
	v_lshlrev_b32_e32 v182, 16, v134
	v_pk_mul_f32 v[134:135], v[184:185], v[184:185]
	v_lshlrev_b32_e32 v178, 16, v132
	v_and_b32_e32 v179, 0xffff0000, v132
	v_lshlrev_b32_e32 v180, 16, v133
	v_lshlrev_b32_e32 v174, 16, v130
	v_pk_fma_f32 v[136:137], v[186:187], v[186:187], v[136:137]
	v_pk_fma_f32 v[134:135], v[182:183], v[182:183], v[134:135]
	v_mul_f32_e32 v139, v178, v178
	v_mul_f32_e32 v141, v179, v179
	v_and_b32_e32 v181, 0xffff0000, v133
	v_mul_f32_e32 v132, v180, v180
	v_mov_b32_e32 v138, v174
	v_mov_b32_e32 v140, v174
	v_pk_add_f32 v[136:137], v[136:137], v[136:137] op_sel_hi:[0,1]
	v_pk_add_f32 v[134:135], v[134:135], v[134:135] op_sel_hi:[0,1]
	v_pk_fma_f32 v[132:133], v[180:181], v[180:181], v[132:133] op_sel_hi:[1,1,0]
	v_and_b32_e32 v175, 0xffff0000, v130
	v_lshlrev_b32_e32 v176, 16, v131
	v_and_b32_e32 v177, 0xffff0000, v131
	v_pk_add_f32 v[138:139], v[138:139], v[140:141]
	v_mul_f32_e32 v132, v175, v175
	v_mul_f32_e32 v134, v176, v176
	v_mul_f32_e32 v136, v177, v177
	v_mul_f32_e32 v130, v174, v174
	v_mov_b32_e32 v131, v139
	v_pk_add_f32 v[130:131], v[130:131], v[132:133]
	v_pk_add_f32 v[132:133], v[134:135], v[136:137]
	s_ashr_i32 s7, s6, 31
	v_pk_add_f32 v[130:131], v[130:131], v[132:133]
	s_cmpk_gt_i32 s6, 0x7fff
	v_add_f32_e32 v130, v130, v131
	s_nop 1
	v_add_f32_dpp v130, v130, v130 quad_perm:[1,0,3,2] row_mask:0xf bank_mask:0xf
	s_nop 1
	v_add_f32_dpp v130, v130, v130 quad_perm:[2,3,0,1] row_mask:0xf bank_mask:0xf
	s_nop 1
	v_add_f32_dpp v130, v130, v130 row_half_mirror row_mask:0xf bank_mask:0xf
	s_nop 1
	v_add_f32_dpp v130, v130, v130 row_mirror row_mask:0xf bank_mask:0xf
	s_nop 1
	v_add_f32_dpp v130, v130, v130 row_bcast:15 row_mask:0xa bank_mask:0xf
	s_nop 1
	v_add_f32_dpp v130, v130, v130 row_bcast:31 row_mask:0xc bank_mask:0xf
	s_nop 0
	v_readlane_b32 s64, v130, 63
	s_nop 1
	v_mov_b32_e32 v130, s64
	s_waitcnt lgkmcnt(0)
	s_mov_b64 s[10:11], -1
	v_fmamk_f32 v130, v130, 0x3a800000, v197
	v_mul_f32_e32 v131, 0x4b800000, v130
	v_cmp_gt_f32_e32 vcc, s22, v130
	s_nop 1
	v_cndmask_b32_e32 v130, v130, v131, vcc
	v_rsq_f32_e32 v130, v130
	s_nop 0
	v_mul_f32_e32 v131, 0x45800000, v130
	v_cndmask_b32_e32 v190, v130, v131, vcc
	s_cbranch_scc0 .Lrow2_2220
	v_mov_b32_e32 v130, v187
	v_mov_b32_e32 v131, v189
	v_mov_b32_e32 v132, v186
	v_mov_b32_e32 v133, v188
	v_pk_mul_f32 v[130:131], v[130:131], v[190:191] op_sel_hi:[1,0]
	v_pk_mul_f32 v[132:133], v[132:133], v[190:191] op_sel_hi:[1,0]
	v_pk_mul_f32 v[130:131], v[4:5], v[130:131]
	v_pk_mul_f32 v[134:135], v[2:3], v[132:133]
	s_waitcnt vmcnt(11)
	v_pk_fma_f32 v[132:133], v[100:101], v[130:131], v[116:117]
	v_pk_fma_f32 v[130:131], v[98:99], v[134:135], v[114:115]
	v_mov_b32_e32 v134, v183
	v_mov_b32_e32 v135, v185
	v_mov_b32_e32 v136, v182
	v_mov_b32_e32 v137, v184
	v_pk_mul_f32 v[134:135], v[134:135], v[190:191] op_sel_hi:[1,0]
	v_pk_mul_f32 v[136:137], v[136:137], v[190:191] op_sel_hi:[1,0]
	v_pk_mul_f32 v[134:135], v[8:9], v[134:135]
	v_pk_mul_f32 v[138:139], v[6:7], v[136:137]
	s_add_i32 s0, s6, 0xffff8000
	s_waitcnt vmcnt(7)
	v_pk_fma_f32 v[136:137], v[104:105], v[134:135], v[120:121]
	v_pk_fma_f32 v[134:135], v[102:103], v[138:139], v[118:119]
	v_pk_mul_f32 v[138:139], v[178:179], v[190:191] op_sel_hi:[1,0]
	v_pk_mul_f32 v[140:141], v[180:181], v[190:191] op_sel_hi:[1,0]
	v_pk_mul_f32 v[142:143], v[176:177], v[190:191] op_sel_hi:[1,0]
	v_pk_mul_f32 v[144:145], v[174:175], v[190:191] op_sel_hi:[1,0]
	s_lshl_b64 s[8:9], s[0:1], 12
	v_pk_mul_f32 v[138:139], v[18:19], v[138:139]
	v_pk_mul_f32 v[140:141], v[20:21], v[140:141]
	v_pk_mul_f32 v[200:201], v[22:23], v[144:145]
	v_pk_mul_f32 v[142:143], v[24:25], v[142:143]
	v_lshl_add_u64 v[198:199], v[164:165], 0, s[8:9]
	s_waitcnt vmcnt(6)
	v_pk_fma_f32 v[140:141], v[108:109], v[140:141], v[124:125]
	v_pk_fma_f32 v[138:139], v[106:107], v[138:139], v[122:123]
	s_waitcnt vmcnt(4)
	v_pk_fma_f32 v[144:145], v[112:113], v[142:143], v[128:129]
	v_pk_fma_f32 v[142:143], v[110:111], v[200:201], v[126:127]
	global_store_dwordx4 v[198:199], v[130:133], off
	global_store_dwordx4 v[198:199], v[134:137], off offset:1024
	global_store_dwordx4 v[198:199], v[138:141], off offset:2048
	global_store_dwordx4 v[198:199], v[142:145], off offset:3072
	s_lshl_b64 s[8:9], s[6:7], 11
	s_mov_b64 s[10:11], 0

; #define GAS __attribute__((address_space(1)))
; DI unsigned pk2(float lo, float hi) { f32x2_t v = {lo, hi}; bf16x2_t b = __builtin_convertvector(v, bf16x2_t); return __builtin_bit_cast(unsigned, b); }
; DI float bflo(unsigned w) { return __uint_as_float(w << 16); }
; DI float bfhi(unsigned w) { return __uint_as_float(w & 0xffff0000u); }
; DI void phase_e(const Ctx& C, int nslab, int has_post, int pl, int ps, float pw, int has_pre, int ql, int qs, int nrows,
;                 const GAS float* xsrc, const GAS float* csrc, GAS float* xdst, GAS float* cdst, bool xs16, bool xd16) {
;     ...
;     for (; i < total; i += 8) {
;         const int row = E_ROW(i);
;         const bool isx = row < MX; const int mi = isx ? (row >> 13) : 4;
;         f32x4 v[4]; u32x2 yw[4];
; #pragma unroll
;         for (int j = 0; j < 4; ++j) { v[j] = vN[j]; yw[j] = yN[j]; vN[j] = vM[j]; yN[j] = yM[j]; }
;         if (i + 16 < total) E_LOAD(i + 16, vM, yM);
;     ...
;             f32x4 y[4]; float ss = 0.f;
; #pragma unroll
;             for (int j = 0; j < 4; ++j) {
;                 if (isx || nslab == 0) { y[j] = (f32x4){bflo(yw[j].x), bfhi(yw[j].x), bflo(yw[j].y), bfhi(yw[j].y)}; }
;                 else { y[j] = (f32x4){0.f, 0.f, 0.f, 0.f};
;                     for (int s = 0; s < nslab; ++s) { const u32x2 w = *(const GAS u32x2*)(YS + ((size_t)s * MC + (row - MX)) * 1024 + 256 * j + 4 * lane); y[j] += (f32x4){bflo(w.x), bfhi(w.x), bflo(w.y), bfhi(w.y)}; } }
;                 ss += (y[j][0] * y[j][0] + y[j][1] * y[j][1]) + (y[j][2] * y[j][2] + y[j][3] * y[j][3]); }
;             const float r = rsqrtf(wave_sum(ss) * (1.0f / 1024.0f) + EPS);
;             if (isx && xd16) { GAS bf16* d16 = (GAS bf16*)xdst + (size_t)row * 1024;
; #pragma unroll
;                 for (int j = 0; j < 4; ++j) { v[j] += pw * gt[j] * ((y[j] * r) * gpo[j]); u32x2 w; w.x = pk2(v[j][0], v[j][1]); w.y = pk2(v[j][2], v[j][3]); __builtin_nontemporal_store(w, (GAS u32x2*)(d16 + 256 * j + 4 * lane));
;                     v[j] = (f32x4){bflo(w.x), bfhi(w.x), bflo(w.y), bfhi(w.y)}; }
;             } else { GAS float* dst = isx ? xdst + (size_t)row * 1024 : cdst + (size_t)(row - MX) * 1024;
; #pragma unroll
;                 for (int j = 0; j < 4; ++j) { v[j] += pw * gt[j] * ((y[j] * r) * gpo[j]); __builtin_nontemporal_store(v[j], (GAS f32x4*)(dst + 256 * j + 4 * lane)); } }
.LBB0_2444:
	v_lshlrev_b32_e32 v123, 16, v107
	v_lshlrev_b32_e32 v122, 16, v106
	v_and_b32_e32 v107, 0xffff0000, v107
	v_and_b32_e32 v106, 0xffff0000, v106
	v_pk_mul_f32 v[124:125], v[106:107], v[106:107]
	v_lshlrev_b32_e32 v127, 16, v109
	v_pk_fma_f32 v[124:125], v[122:123], v[122:123], v[124:125]
	v_lshlrev_b32_e32 v126, 16, v108
	v_and_b32_e32 v109, 0xffff0000, v109
	v_and_b32_e32 v108, 0xffff0000, v108
	v_pk_add_f32 v[124:125], v[124:125], v[124:125] op_sel_hi:[0,1]
	v_pk_mul_f32 v[128:129], v[108:109], v[108:109]
	v_lshlrev_b32_e32 v130, 16, v110
	v_and_b32_e32 v131, 0xffff0000, v110
	v_lshlrev_b32_e32 v110, 16, v111
	v_lshlrev_b32_e32 v132, 16, v112
	v_pk_fma_f32 v[128:129], v[126:127], v[126:127], v[128:129]
	v_mul_f32_e32 v133, v130, v130
	v_mul_f32_e32 v135, v131, v131
	v_and_b32_e32 v111, 0xffff0000, v111
	v_mul_f32_e32 v124, v110, v110
	v_mov_b32_e32 v134, v132
	v_pk_add_f32 v[128:129], v[128:129], v[128:129] op_sel_hi:[0,1]
	v_pk_fma_f32 v[136:137], v[110:111], v[110:111], v[124:125] op_sel_hi:[1,1,0]
	v_and_b32_e32 v121, 0xffff0000, v112
	v_lshlrev_b32_e32 v112, 16, v113
	v_and_b32_e32 v113, 0xffff0000, v113
	v_pk_add_f32 v[134:135], v[132:133], v[134:135]
	v_mul_f32_e32 v136, v121, v121
	v_mul_f32_e32 v128, v112, v112
	v_mul_f32_e32 v124, v113, v113
	v_mul_f32_e32 v138, v132, v132
	v_mov_b32_e32 v139, v135
	v_pk_add_f32 v[134:135], v[138:139], v[136:137]
	v_pk_add_f32 v[124:125], v[128:129], v[124:125]
	s_add_i32 s2, s19, 0xffff8000
	v_pk_add_f32 v[124:125], v[134:135], v[124:125]
	s_ashr_i32 s6, s19, 31
	v_add_f32_e32 v124, v124, v125
	s_nop 1
	v_add_f32_dpp v124, v124, v124 quad_perm:[1,0,3,2] row_mask:0xf bank_mask:0xf
	s_nop 1
	v_add_f32_dpp v124, v124, v124 quad_perm:[2,3,0,1] row_mask:0xf bank_mask:0xf
	s_nop 1
	v_add_f32_dpp v124, v124, v124 row_half_mirror row_mask:0xf bank_mask:0xf
	s_nop 1
	v_add_f32_dpp v124, v124, v124 row_mirror row_mask:0xf bank_mask:0xf
	s_nop 1
	v_add_f32_dpp v124, v124, v124 row_bcast:15 row_mask:0xa bank_mask:0xf
	s_nop 1
	v_add_f32_dpp v124, v124, v124 row_bcast:31 row_mask:0xc bank_mask:0xf
	s_nop 0
	v_readlane_b32 s64, v124, 63
	s_nop 1
	v_mov_b32_e32 v124, s64
	s_waitcnt lgkmcnt(0)
	s_cmp_lt_i32 s19, 0x8000
	v_mov_b32_e32 v136, v123
	v_mov_b32_e32 v123, v106
	s_cselect_b32 s7, s6, 0
	s_cselect_b32 s6, s19, s2
	v_mov_b32_e32 v137, v107
	s_cselect_b32 s2, s75, s1
	s_cselect_b32 s8, s74, s0
	s_lshl_b64 s[6:7], s[6:7], 12
	s_waitcnt vmcnt(1)
	v_pk_mul_f32 v[134:135], v[50:51], 0.5 op_sel_hi:[1,0]
	s_add_u32 s6, s8, s6
	v_pk_mul_f32 v[128:129], v[52:53], 0.5 op_sel_hi:[1,0]
	s_addc_u32 s7, s2, s7
	v_mov_b32_e32 v133, v121
	s_add_i32 s14, s14, 8
	s_cmp_lt_i32 s14, s15
	v_fmamk_f32 v124, v124, 0x3a800000, v120
	v_mul_f32_e32 v125, 0x4b800000, v124
	v_cmp_gt_f32_e32 vcc, s18, v124
	s_nop 1
	v_cndmask_b32_e32 v124, v124, v125, vcc
	v_rsq_f32_e32 v124, v124
	s_nop 0
	v_mul_f32_e32 v125, 0x45800000, v124
	v_cndmask_b32_e32 v124, v124, v125, vcc
	v_pk_mul_f32 v[106:107], v[122:123], v[124:125] op_sel_hi:[1,0]
	v_pk_mul_f32 v[136:137], v[136:137], v[124:125] op_sel_hi:[1,0]
	v_pk_mul_f32 v[106:107], v[2:3], v[106:107]
	v_pk_mul_f32 v[122:123], v[4:5], v[136:137]
	v_pk_fma_f32 v[66:67], v[134:135], v[106:107], v[66:67]
	v_mov_b32_e32 v106, v127
	v_mov_b32_e32 v107, v109
	v_mov_b32_e32 v127, v108
	v_pk_fma_f32 v[68:69], v[128:129], v[122:123], v[68:69]
	v_pk_mul_f32 v[106:107], v[106:107], v[124:125] op_sel_hi:[1,0]
	v_pk_mul_f32 v[108:109], v[126:127], v[124:125] op_sel_hi:[1,0]
	global_store_dwordx4 v82, v[66:69], s[6:7]
	v_pk_mul_f32 v[108:109], v[6:7], v[108:109]
	v_pk_mul_f32 v[106:107], v[8:9], v[106:107]
	v_pk_mul_f32 v[66:67], v[56:57], 0.5 op_sel_hi:[1,0]
	v_pk_mul_f32 v[68:69], v[54:55], 0.5 op_sel_hi:[1,0]
	v_pk_fma_f32 v[72:73], v[66:67], v[106:107], v[72:73]
	v_pk_fma_f32 v[70:71], v[68:69], v[108:109], v[70:71]
	v_pk_mul_f32 v[66:67], v[110:111], v[124:125] op_sel_hi:[1,0]
	v_pk_mul_f32 v[68:69], v[130:131], v[124:125] op_sel_hi:[1,0]
	global_store_dwordx4 v82, v[70:73], s[6:7] offset:1024
	v_pk_mul_f32 v[68:69], v[10:11], v[68:69]
	v_pk_mul_f32 v[66:67], v[12:13], v[66:67]
	v_pk_mul_f32 v[70:71], v[60:61], 0.5 op_sel_hi:[1,0]
	v_pk_mul_f32 v[72:73], v[58:59], 0.5 op_sel_hi:[1,0]
	v_pk_fma_f32 v[76:77], v[70:71], v[66:67], v[76:77]
	v_pk_fma_f32 v[74:75], v[72:73], v[68:69], v[74:75]
	v_pk_mul_f32 v[70:71], v[112:113], v[124:125] op_sel_hi:[1,0]
	v_pk_mul_f32 v[72:73], v[132:133], v[124:125] op_sel_hi:[1,0]
	global_store_dwordx4 v82, v[74:77], s[6:7] offset:2048
	v_pk_mul_f32 v[72:73], v[14:15], v[72:73]
	v_pk_mul_f32 v[70:71], v[16:17], v[70:71]
	s_waitcnt vmcnt(3)
	v_pk_mul_f32 v[74:75], v[64:65], 0.5 op_sel_hi:[1,0]
	v_pk_mul_f32 v[76:77], v[62:63], 0.5 op_sel_hi:[1,0]
	v_pk_fma_f32 v[80:81], v[74:75], v[70:71], v[80:81]
	v_pk_fma_f32 v[78:79], v[76:77], v[72:73], v[78:79]
	global_store_dwordx4 v82, v[78:81], s[6:7] offset:3072
	s_mov_b64 vcc, s[98:99]
	s_cbranch_vccz .Leload_skip2_4
	s_waitcnt vmcnt(4)
	v_lshlrev_b32_e32 v34, 16, v36
	v_and_b32_e32 v35, 0xffff0000, v36
	v_lshlrev_b32_e32 v36, 16, v37
	v_and_b32_e32 v37, 0xffff0000, v37
	v_lshlrev_b32_e32 v38, 16, v40
	v_and_b32_e32 v39, 0xffff0000, v40
	v_lshlrev_b32_e32 v40, 16, v41
	v_and_b32_e32 v41, 0xffff0000, v41
	v_lshlrev_b32_e32 v42, 16, v44
	v_and_b32_e32 v43, 0xffff0000, v44
	v_lshlrev_b32_e32 v44, 16, v45
	v_and_b32_e32 v45, 0xffff0000, v45
	v_lshlrev_b32_e32 v46, 16, v48
	v_and_b32_e32 v47, 0xffff0000, v48
	v_lshlrev_b32_e32 v48, 16, v49
	v_and_b32_e32 v49, 0xffff0000, v49

; #define GAS __attribute__((address_space(1)))
; DI unsigned pk2(float lo, float hi) { f32x2_t v = {lo, hi}; bf16x2_t b = __builtin_convertvector(v, bf16x2_t); return __builtin_bit_cast(unsigned, b); }
; DI float bflo(unsigned w) { return __uint_as_float(w << 16); }
; DI float bfhi(unsigned w) { return __uint_as_float(w & 0xffff0000u); }
; DI void phase_e(const Ctx& C, int nslab, int has_post, int pl, int ps, float pw, int has_pre, int ql, int qs, int nrows,
;                 const GAS float* xsrc, const GAS float* csrc, GAS float* xdst, GAS float* cdst, bool xs16, bool xd16) {
;     ...
;             f32x4 y[4]; float ss = 0.f;
; #pragma unroll
;             for (int j = 0; j < 4; ++j) {
;                 if (isx || nslab == 0) { y[j] = (f32x4){bflo(yw[j].x), bfhi(yw[j].x), bflo(yw[j].y), bfhi(yw[j].y)}; }
;                 else { y[j] = (f32x4){0.f, 0.f, 0.f, 0.f};
;                     for (int s = 0; s < nslab; ++s) { const u32x2 w = *(const GAS u32x2*)(YS + ((size_t)s * MC + (row - MX)) * 1024 + 256 * j + 4 * lane); y[j] += (f32x4){bflo(w.x), bfhi(w.x), bflo(w.y), bfhi(w.y)}; } }
;                 ss += (y[j][0] * y[j][0] + y[j][1] * y[j][1]) + (y[j][2] * y[j][2] + y[j][3] * y[j][3]); }
;             const float r = rsqrtf(wave_sum(ss) * (1.0f / 1024.0f) + EPS);
;             if (isx && xd16) { GAS bf16* d16 = (GAS bf16*)xdst + (size_t)row * 1024;
; #pragma unroll
;                 for (int j = 0; j < 4; ++j) { v[j] += pw * gt[j] * ((y[j] * r) * gpo[j]); u32x2 w; w.x = pk2(v[j][0], v[j][1]); w.y = pk2(v[j][2], v[j][3]); __builtin_nontemporal_store(w, (GAS u32x2*)(d16 + 256 * j + 4 * lane));
;                     v[j] = (f32x4){bflo(w.x), bfhi(w.x), bflo(w.y), bfhi(w.y)}; }
;             } else { GAS float* dst = isx ? xdst + (size_t)row * 1024 : cdst + (size_t)(row - MX) * 1024;
; #pragma unroll
;                 for (int j = 0; j < 4; ++j) { v[j] += pw * gt[j] * ((y[j] * r) * gpo[j]); __builtin_nontemporal_store(v[j], (GAS f32x4*)(dst + 256 * j + 4 * lane)); } }
.LBB0_2444_u0:
	v_lshlrev_b32_e32 v123, 16, v99
	v_lshlrev_b32_e32 v122, 16, v98
	v_and_b32_e32 v99, 0xffff0000, v99
	v_and_b32_e32 v98, 0xffff0000, v98
	v_pk_mul_f32 v[124:125], v[98:99], v[98:99]
	v_lshlrev_b32_e32 v127, 16, v91
	v_pk_fma_f32 v[124:125], v[122:123], v[122:123], v[124:125]
	v_lshlrev_b32_e32 v126, 16, v90
	v_and_b32_e32 v91, 0xffff0000, v91
	v_and_b32_e32 v90, 0xffff0000, v90
	v_pk_add_f32 v[124:125], v[124:125], v[124:125] op_sel_hi:[0,1]
	v_pk_mul_f32 v[128:129], v[90:91], v[90:91]
	v_lshlrev_b32_e32 v130, 16, v86
	v_and_b32_e32 v131, 0xffff0000, v86
	v_lshlrev_b32_e32 v86, 16, v87
	v_lshlrev_b32_e32 v132, 16, v84
	v_pk_fma_f32 v[128:129], v[126:127], v[126:127], v[128:129]
	v_mul_f32_e32 v133, v130, v130
	v_mul_f32_e32 v135, v131, v131
	v_and_b32_e32 v87, 0xffff0000, v87
	v_mul_f32_e32 v124, v86, v86
	v_mov_b32_e32 v134, v132
	v_pk_add_f32 v[128:129], v[128:129], v[128:129] op_sel_hi:[0,1]
	v_pk_fma_f32 v[136:137], v[86:87], v[86:87], v[124:125] op_sel_hi:[1,1,0]
	v_and_b32_e32 v121, 0xffff0000, v84
	v_lshlrev_b32_e32 v84, 16, v85
	v_and_b32_e32 v85, 0xffff0000, v85
	v_pk_add_f32 v[134:135], v[132:133], v[134:135]
	v_mul_f32_e32 v136, v121, v121
	v_mul_f32_e32 v128, v84, v84
	v_mul_f32_e32 v124, v85, v85
	v_mul_f32_e32 v138, v132, v132
	v_mov_b32_e32 v139, v135
	v_pk_add_f32 v[134:135], v[138:139], v[136:137]
	v_pk_add_f32 v[124:125], v[128:129], v[124:125]
	s_add_i32 s2, s19, 0xffff8000
	v_pk_add_f32 v[124:125], v[134:135], v[124:125]
	s_ashr_i32 s6, s19, 31
	v_add_f32_e32 v124, v124, v125
	s_nop 1
	v_add_f32_dpp v124, v124, v124 quad_perm:[1,0,3,2] row_mask:0xf bank_mask:0xf
	s_nop 1
	v_add_f32_dpp v124, v124, v124 quad_perm:[2,3,0,1] row_mask:0xf bank_mask:0xf
	s_nop 1
	v_add_f32_dpp v124, v124, v124 row_half_mirror row_mask:0xf bank_mask:0xf
	s_nop 1
	v_add_f32_dpp v124, v124, v124 row_mirror row_mask:0xf bank_mask:0xf
	s_nop 1
	v_add_f32_dpp v124, v124, v124 row_bcast:15 row_mask:0xa bank_mask:0xf
	s_nop 1
	v_add_f32_dpp v124, v124, v124 row_bcast:31 row_mask:0xc bank_mask:0xf
	s_nop 0
	v_readlane_b32 s64, v124, 63
	s_nop 1
	v_mov_b32_e32 v124, s64
	s_waitcnt lgkmcnt(0)
	s_cmp_lt_i32 s19, 0x8000
	v_mov_b32_e32 v136, v123
	v_mov_b32_e32 v123, v98
	s_cselect_b32 s7, s6, 0
	s_cselect_b32 s6, s19, s2
	v_mov_b32_e32 v137, v99
	s_cselect_b32 s2, s75, s1
	s_cselect_b32 s8, s74, s0
	s_lshl_b64 s[6:7], s[6:7], 12
	s_waitcnt vmcnt(1)
	v_pk_mul_f32 v[134:135], v[50:51], 0.5 op_sel_hi:[1,0]
	s_add_u32 s6, s8, s6
	v_pk_mul_f32 v[128:129], v[52:53], 0.5 op_sel_hi:[1,0]
	s_addc_u32 s7, s2, s7
	v_mov_b32_e32 v133, v121
	s_add_i32 s14, s14, 8
	s_cmp_lt_i32 s14, s15
	v_fmamk_f32 v124, v124, 0x3a800000, v120
	v_mul_f32_e32 v125, 0x4b800000, v124
	v_cmp_gt_f32_e32 vcc, s18, v124
	s_nop 1
	v_cndmask_b32_e32 v124, v124, v125, vcc
	v_rsq_f32_e32 v124, v124
	s_nop 0
	v_mul_f32_e32 v125, 0x45800000, v124
	v_cndmask_b32_e32 v124, v124, v125, vcc
	v_pk_mul_f32 v[98:99], v[122:123], v[124:125] op_sel_hi:[1,0]
	v_pk_mul_f32 v[136:137], v[136:137], v[124:125] op_sel_hi:[1,0]
	v_pk_mul_f32 v[98:99], v[2:3], v[98:99]
	v_pk_mul_f32 v[122:123], v[4:5], v[136:137]
	v_pk_fma_f32 v[30:31], v[134:135], v[98:99], v[30:31]
	v_mov_b32_e32 v98, v127
	v_mov_b32_e32 v99, v91
	v_mov_b32_e32 v127, v90
	v_pk_fma_f32 v[32:33], v[128:129], v[122:123], v[32:33]
	v_pk_mul_f32 v[98:99], v[98:99], v[124:125] op_sel_hi:[1,0]
	v_pk_mul_f32 v[90:91], v[126:127], v[124:125] op_sel_hi:[1,0]
	global_store_dwordx4 v82, v[30:33], s[6:7]
	v_pk_mul_f32 v[90:91], v[6:7], v[90:91]
	v_pk_mul_f32 v[98:99], v[8:9], v[98:99]
	v_pk_mul_f32 v[30:31], v[56:57], 0.5 op_sel_hi:[1,0]
	v_pk_mul_f32 v[32:33], v[54:55], 0.5 op_sel_hi:[1,0]
	v_pk_fma_f32 v[28:29], v[30:31], v[98:99], v[28:29]
	v_pk_fma_f32 v[26:27], v[32:33], v[90:91], v[26:27]
	v_pk_mul_f32 v[30:31], v[86:87], v[124:125] op_sel_hi:[1,0]
	v_pk_mul_f32 v[32:33], v[130:131], v[124:125] op_sel_hi:[1,0]
	global_store_dwordx4 v82, v[26:29], s[6:7] offset:1024
	v_pk_mul_f32 v[32:33], v[10:11], v[32:33]
	v_pk_mul_f32 v[30:31], v[12:13], v[30:31]
	v_pk_mul_f32 v[26:27], v[60:61], 0.5 op_sel_hi:[1,0]
	v_pk_mul_f32 v[28:29], v[58:59], 0.5 op_sel_hi:[1,0]
	v_pk_fma_f32 v[24:25], v[26:27], v[30:31], v[24:25]
	v_pk_fma_f32 v[22:23], v[28:29], v[32:33], v[22:23]
	v_pk_mul_f32 v[26:27], v[84:85], v[124:125] op_sel_hi:[1,0]
	v_pk_mul_f32 v[28:29], v[132:133], v[124:125] op_sel_hi:[1,0]
	global_store_dwordx4 v82, v[22:25], s[6:7] offset:2048
	v_pk_mul_f32 v[28:29], v[14:15], v[28:29]
	v_pk_mul_f32 v[26:27], v[16:17], v[26:27]
	s_waitcnt vmcnt(3)
	v_pk_mul_f32 v[22:23], v[64:65], 0.5 op_sel_hi:[1,0]
	v_pk_mul_f32 v[24:25], v[62:63], 0.5 op_sel_hi:[1,0]
	v_pk_fma_f32 v[20:21], v[22:23], v[26:27], v[20:21]
	v_pk_fma_f32 v[18:19], v[24:25], v[28:29], v[18:19]
	global_store_dwordx4 v82, v[18:21], s[6:7] offset:3072
	s_mov_b64 vcc, s[98:99]
	s_cbranch_vccz .Leload_skip_4
	s_waitcnt vmcnt(4)
	v_lshlrev_b32_e32 v66, 16, v68
	v_and_b32_e32 v67, 0xffff0000, v68
	v_lshlrev_b32_e32 v68, 16, v69
	v_and_b32_e32 v69, 0xffff0000, v69
	v_lshlrev_b32_e32 v70, 16, v72
	v_and_b32_e32 v71, 0xffff0000, v72
	v_lshlrev_b32_e32 v72, 16, v73
	v_and_b32_e32 v73, 0xffff0000, v73
	v_lshlrev_b32_e32 v74, 16, v76
	v_and_b32_e32 v75, 0xffff0000, v76
	v_lshlrev_b32_e32 v76, 16, v77
	v_and_b32_e32 v77, 0xffff0000, v77
	v_lshlrev_b32_e32 v78, 16, v80
	v_and_b32_e32 v79, 0xffff0000, v80
	v_lshlrev_b32_e32 v80, 16, v81
	v_and_b32_e32 v81, 0xffff0000, v81

; #define GAS __attribute__((address_space(1)))
; DI unsigned pk2(float lo, float hi) { f32x2_t v = {lo, hi}; bf16x2_t b = __builtin_convertvector(v, bf16x2_t); return __builtin_bit_cast(unsigned, b); }
; DI float bflo(unsigned w) { return __uint_as_float(w << 16); }
; DI float bfhi(unsigned w) { return __uint_as_float(w & 0xffff0000u); }
; DI void phase_e(const Ctx& C, int nslab, int has_post, int pl, int ps, float pw, int has_pre, int ql, int qs, int nrows,
;                 const GAS float* xsrc, const GAS float* csrc, GAS float* xdst, GAS float* cdst, bool xs16, bool xd16) {
;     ...
;             f32x4 y[4]; float ss = 0.f;
; #pragma unroll
;             for (int j = 0; j < 4; ++j) {
;                 if (isx || nslab == 0) { y[j] = (f32x4){bflo(yw[j].x), bfhi(yw[j].x), bflo(yw[j].y), bfhi(yw[j].y)}; }
;                 else { y[j] = (f32x4){0.f, 0.f, 0.f, 0.f};
;                     for (int s = 0; s < nslab; ++s) { const u32x2 w = *(const GAS u32x2*)(YS + ((size_t)s * MC + (row - MX)) * 1024 + 256 * j + 4 * lane); y[j] += (f32x4){bflo(w.x), bfhi(w.x), bflo(w.y), bfhi(w.y)}; } }
;                 ss += (y[j][0] * y[j][0] + y[j][1] * y[j][1]) + (y[j][2] * y[j][2] + y[j][3] * y[j][3]); }
;             const float r = rsqrtf(wave_sum(ss) * (1.0f / 1024.0f) + EPS);
;             if (isx && xd16) { GAS bf16* d16 = (GAS bf16*)xdst + (size_t)row * 1024;
; #pragma unroll
;                 for (int j = 0; j < 4; ++j) { v[j] += pw * gt[j] * ((y[j] * r) * gpo[j]); u32x2 w; w.x = pk2(v[j][0], v[j][1]); w.y = pk2(v[j][2], v[j][3]); __builtin_nontemporal_store(w, (GAS u32x2*)(d16 + 256 * j + 4 * lane));
;                     v[j] = (f32x4){bflo(w.x), bfhi(w.x), bflo(w.y), bfhi(w.y)}; }
;             } else { GAS float* dst = isx ? xdst + (size_t)row * 1024 : cdst + (size_t)(row - MX) * 1024;
; #pragma unroll
;                 for (int j = 0; j < 4; ++j) { v[j] += pw * gt[j] * ((y[j] * r) * gpo[j]); __builtin_nontemporal_store(v[j], (GAS f32x4*)(dst + 256 * j + 4 * lane)); } }
.Lrow1_2444:
	v_lshlrev_b32_e32 v123, 16, v89
	v_lshlrev_b32_e32 v122, 16, v88
	v_and_b32_e32 v89, 0xffff0000, v89
	v_and_b32_e32 v88, 0xffff0000, v88
	v_pk_mul_f32 v[124:125], v[88:89], v[88:89]
	v_lshlrev_b32_e32 v127, 16, v93
	v_pk_fma_f32 v[124:125], v[122:123], v[122:123], v[124:125]
	v_lshlrev_b32_e32 v126, 16, v92
	v_and_b32_e32 v93, 0xffff0000, v93
	v_and_b32_e32 v92, 0xffff0000, v92
	v_pk_add_f32 v[124:125], v[124:125], v[124:125] op_sel_hi:[0,1]
	v_pk_mul_f32 v[128:129], v[92:93], v[92:93]
	v_lshlrev_b32_e32 v130, 16, v94
	v_and_b32_e32 v131, 0xffff0000, v94
	v_lshlrev_b32_e32 v94, 16, v95
	v_lshlrev_b32_e32 v132, 16, v96
	v_pk_fma_f32 v[128:129], v[126:127], v[126:127], v[128:129]
	v_mul_f32_e32 v133, v130, v130
	v_mul_f32_e32 v135, v131, v131
	v_and_b32_e32 v95, 0xffff0000, v95
	v_mul_f32_e32 v124, v94, v94
	v_mov_b32_e32 v134, v132
	v_pk_add_f32 v[128:129], v[128:129], v[128:129] op_sel_hi:[0,1]
	v_pk_fma_f32 v[136:137], v[94:95], v[94:95], v[124:125] op_sel_hi:[1,1,0]
	v_and_b32_e32 v121, 0xffff0000, v96
	v_lshlrev_b32_e32 v96, 16, v97
	v_and_b32_e32 v97, 0xffff0000, v97
	v_pk_add_f32 v[134:135], v[132:133], v[134:135]
	v_mul_f32_e32 v136, v121, v121
	v_mul_f32_e32 v128, v96, v96
	v_mul_f32_e32 v124, v97, v97
	v_mul_f32_e32 v138, v132, v132
	v_mov_b32_e32 v139, v135
	v_pk_add_f32 v[134:135], v[138:139], v[136:137]
	v_pk_add_f32 v[124:125], v[128:129], v[124:125]
	s_add_i32 s2, s19, 0xffff8000
	v_pk_add_f32 v[124:125], v[134:135], v[124:125]
	s_ashr_i32 s6, s19, 31
	v_add_f32_e32 v124, v124, v125
	s_nop 1
	v_add_f32_dpp v124, v124, v124 quad_perm:[1,0,3,2] row_mask:0xf bank_mask:0xf
	s_nop 1
	v_add_f32_dpp v124, v124, v124 quad_perm:[2,3,0,1] row_mask:0xf bank_mask:0xf
	s_nop 1
	v_add_f32_dpp v124, v124, v124 row_half_mirror row_mask:0xf bank_mask:0xf
	s_nop 1
	v_add_f32_dpp v124, v124, v124 row_mirror row_mask:0xf bank_mask:0xf
	s_nop 1
	v_add_f32_dpp v124, v124, v124 row_bcast:15 row_mask:0xa bank_mask:0xf
	s_nop 1
	v_add_f32_dpp v124, v124, v124 row_bcast:31 row_mask:0xc bank_mask:0xf
	s_nop 0
	v_readlane_b32 s64, v124, 63
	s_nop 1
	v_mov_b32_e32 v124, s64
	s_waitcnt lgkmcnt(0)
	s_cmp_lt_i32 s19, 0x8000
	v_mov_b32_e32 v136, v123
	v_mov_b32_e32 v123, v88
	s_cselect_b32 s7, s6, 0
	s_cselect_b32 s6, s19, s2
	v_mov_b32_e32 v137, v89
	s_cselect_b32 s2, s75, s1
	s_cselect_b32 s8, s74, s0
	s_lshl_b64 s[6:7], s[6:7], 12
	s_waitcnt vmcnt(1)
	v_pk_mul_f32 v[134:135], v[50:51], 0.5 op_sel_hi:[1,0]
	s_add_u32 s6, s8, s6
	v_pk_mul_f32 v[128:129], v[52:53], 0.5 op_sel_hi:[1,0]
	s_addc_u32 s7, s2, s7
	v_mov_b32_e32 v133, v121
	s_add_i32 s14, s14, 8
	s_cmp_lt_i32 s14, s15
	v_fmamk_f32 v124, v124, 0x3a800000, v120
	v_mul_f32_e32 v125, 0x4b800000, v124
	v_cmp_gt_f32_e32 vcc, s18, v124
	s_nop 1
	v_cndmask_b32_e32 v124, v124, v125, vcc
	v_rsq_f32_e32 v124, v124
	s_nop 0
	v_mul_f32_e32 v125, 0x45800000, v124
	v_cndmask_b32_e32 v124, v124, v125, vcc
	v_pk_mul_f32 v[88:89], v[122:123], v[124:125] op_sel_hi:[1,0]
	v_pk_mul_f32 v[136:137], v[136:137], v[124:125] op_sel_hi:[1,0]
	v_pk_mul_f32 v[88:89], v[2:3], v[88:89]
	v_pk_mul_f32 v[122:123], v[4:5], v[136:137]
	v_pk_fma_f32 v[34:35], v[134:135], v[88:89], v[34:35]
	v_mov_b32_e32 v88, v127
	v_mov_b32_e32 v89, v93
	v_mov_b32_e32 v127, v92
	v_pk_fma_f32 v[36:37], v[128:129], v[122:123], v[36:37]
	v_pk_mul_f32 v[88:89], v[88:89], v[124:125] op_sel_hi:[1,0]
	v_pk_mul_f32 v[92:93], v[126:127], v[124:125] op_sel_hi:[1,0]
	global_store_dwordx4 v82, v[34:37], s[6:7]
	v_pk_mul_f32 v[92:93], v[6:7], v[92:93]
	v_pk_mul_f32 v[88:89], v[8:9], v[88:89]
	v_pk_mul_f32 v[34:35], v[56:57], 0.5 op_sel_hi:[1,0]
	v_pk_mul_f32 v[36:37], v[54:55], 0.5 op_sel_hi:[1,0]
	v_pk_fma_f32 v[40:41], v[34:35], v[88:89], v[40:41]
	v_pk_fma_f32 v[38:39], v[36:37], v[92:93], v[38:39]
	v_pk_mul_f32 v[34:35], v[94:95], v[124:125] op_sel_hi:[1,0]
	v_pk_mul_f32 v[36:37], v[130:131], v[124:125] op_sel_hi:[1,0]
	global_store_dwordx4 v82, v[38:41], s[6:7] offset:1024
	v_pk_mul_f32 v[36:37], v[10:11], v[36:37]
	v_pk_mul_f32 v[34:35], v[12:13], v[34:35]
	v_pk_mul_f32 v[38:39], v[60:61], 0.5 op_sel_hi:[1,0]
	v_pk_mul_f32 v[40:41], v[58:59], 0.5 op_sel_hi:[1,0]
	v_pk_fma_f32 v[44:45], v[38:39], v[34:35], v[44:45]
	v_pk_fma_f32 v[42:43], v[40:41], v[36:37], v[42:43]
	v_pk_mul_f32 v[38:39], v[96:97], v[124:125] op_sel_hi:[1,0]
	v_pk_mul_f32 v[40:41], v[132:133], v[124:125] op_sel_hi:[1,0]
	global_store_dwordx4 v82, v[42:45], s[6:7] offset:2048
	v_pk_mul_f32 v[40:41], v[14:15], v[40:41]
	v_pk_mul_f32 v[38:39], v[16:17], v[38:39]
	s_waitcnt vmcnt(3)
	v_pk_mul_f32 v[42:43], v[64:65], 0.5 op_sel_hi:[1,0]
	v_pk_mul_f32 v[44:45], v[62:63], 0.5 op_sel_hi:[1,0]
	v_pk_fma_f32 v[48:49], v[42:43], v[38:39], v[48:49]
	v_pk_fma_f32 v[46:47], v[44:45], v[40:41], v[46:47]
	global_store_dwordx4 v82, v[46:49], s[6:7] offset:3072
	s_mov_b64 vcc, s[98:99]
	s_cbranch_vccz .Leload_skip1_4
	s_waitcnt vmcnt(4)
	v_lshlrev_b32_e32 v30, 16, v32
	v_and_b32_e32 v31, 0xffff0000, v32
	v_lshlrev_b32_e32 v32, 16, v33
	v_and_b32_e32 v33, 0xffff0000, v33
	v_lshlrev_b32_e32 v26, 16, v28
	v_and_b32_e32 v27, 0xffff0000, v28
	v_lshlrev_b32_e32 v28, 16, v29
	v_and_b32_e32 v29, 0xffff0000, v29
	v_lshlrev_b32_e32 v22, 16, v24
	v_and_b32_e32 v23, 0xffff0000, v24
	v_lshlrev_b32_e32 v24, 16, v25
	v_and_b32_e32 v25, 0xffff0000, v25
	v_lshlrev_b32_e32 v18, 16, v20
	v_and_b32_e32 v19, 0xffff0000, v20
	v_lshlrev_b32_e32 v20, 16, v21
	v_and_b32_e32 v21, 0xffff0000, v21
